# conv_item LDS read-back: 8 reads + one wait + 4 cvts per 16-byte store instead of 4 read-pair/wait/cvt quads (28 groups)
# baseline (speedup 1.0000x reference)
; __device__ __forceinline__ void conv_item(const float* W, int K, int N, int kind, int item, const float* gain, unsigned char* Wb, float* scr, int lane) {
;     const int nblk = N / 32, kb = item / nblk, nb = item - kb * nblk, k0 = 64 * kb, n0 = 32 * nb;
;     float wv_[32];
; #pragma unroll
;     for (int i = 0; i < 32; ++i) wv_[i] = W[(size_t)(k0 + 2 * i + (lane >> 5)) * N + n0 + (lane & 31)];
; __global__ void __launch_bounds__(512, 2) mk_fwd(Args a) {
;     ...
;                     if (r < 512) { conv_item(ap->in[16] + L * 1024 * 1024, 1024, 1024, 10, r, nullptr, Wb, scr, lane); continue; } r -= 512;
;                     if (r < 256) { conv_item(ap->in[11] + L * 512 * 1024, 512, 1024, 7, r, nullptr, Wb, scr, lane); continue; } r -= 256;
;                     if (r < 256) { conv_item(ap->in[13] + L * 512 * 1024, 512, 1024, 8, r, nullptr, Wb, scr, lane); continue; } r -= 256;
;                     if (r < 256) { conv_item(ap->in[15] + L * 512 * 1024, 512, 1024, 9, r, nullptr, Wb, scr, lane); continue; } r -= 256;
.LBB0_303:
	s_andn2_b64 vcc, exec, s[4:5]
	s_cbranch_vccnz .LBB0_305
	s_lshl_b32 s4, s76, 5
	s_and_b32 s6, s4, 0xfffffc00
	v_readlane_b32 s4, v254, 40
	v_readlane_b32 s5, v254, 41
	s_load_dwordx2 s[4:5], s[4:5], 0x78
	s_lshl_b32 s7, s73, 1
	v_lshlrev_b32_e32 v0, 2, v4
	s_waitcnt lgkmcnt(0)
	s_add_u32 s12, s4, s44
	s_addc_u32 s13, s5, s45
	s_add_i32 s4, s7, 0x2c0
	s_and_b32 s92, s4, 0xffffffc0
	s_sub_i32 s4, s75, s6
	s_add_i32 s4, s4, 0xfff9f600
	s_ashr_i32 s5, s4, 31
	s_lshl_b64 s[6:7], s[4:5], 2
	s_add_u32 s6, s12, s6
	v_or_b32_e32 v10, s92, v3
	s_addc_u32 s7, s13, s7
	v_lshl_add_u64 v[8:9], s[6:7], 0, v[0:1]
	v_lshlrev_b32_e32 v0, 10, v10
	v_lshl_add_u64 v[8:9], v[0:1], 2, v[8:9]
	s_movk_i32 s5, 0x2000
	v_add_co_u32_e32 v10, vcc, s5, v8
	s_movk_i32 s5, 0x4000
	s_nop 0
	v_addc_co_u32_e32 v11, vcc, 0, v9, vcc
	global_load_dword v0, v[8:9], off
	global_load_dword v12, v[10:11], off
	v_add_co_u32_e32 v10, vcc, s5, v8
	s_movk_i32 s5, 0x6000
	s_nop 0
	v_addc_co_u32_e32 v11, vcc, 0, v9, vcc
	global_load_dword v13, v[10:11], off
	v_add_co_u32_e32 v10, vcc, s5, v8
	s_mov_b32 s5, 0x8000
	s_nop 0
	v_addc_co_u32_e32 v11, vcc, 0, v9, vcc
	global_load_dword v14, v[10:11], off
	v_add_co_u32_e32 v10, vcc, s5, v8
	s_mov_b32 s5, 0xa000
	s_nop 0
	v_addc_co_u32_e32 v11, vcc, 0, v9, vcc
	global_load_dword v15, v[10:11], off
	v_add_co_u32_e32 v10, vcc, s5, v8
	s_mov_b32 s5, 0xc000
	s_nop 0
	v_addc_co_u32_e32 v11, vcc, 0, v9, vcc
	global_load_dword v16, v[10:11], off
	v_add_co_u32_e32 v10, vcc, s5, v8
	s_mov_b32 s5, 0xe000
	s_nop 0
	v_addc_co_u32_e32 v11, vcc, 0, v9, vcc
	global_load_dword v17, v[10:11], off
	v_add_co_u32_e32 v10, vcc, s5, v8
	s_mov_b32 s5, 0x10000
	s_nop 0
	v_addc_co_u32_e32 v11, vcc, 0, v9, vcc
	global_load_dword v18, v[10:11], off
	v_add_co_u32_e32 v10, vcc, s5, v8
	s_mov_b32 s5, 0x12000
	s_nop 0
	v_addc_co_u32_e32 v11, vcc, 0, v9, vcc
	global_load_dword v19, v[10:11], off
	v_add_co_u32_e32 v10, vcc, s5, v8
	s_mov_b32 s5, 0x14000
	s_nop 0
	v_addc_co_u32_e32 v11, vcc, 0, v9, vcc
	global_load_dword v20, v[10:11], off
	v_add_co_u32_e32 v10, vcc, s5, v8
	s_mov_b32 s5, 0x16000
	s_nop 0
	v_addc_co_u32_e32 v11, vcc, 0, v9, vcc
	global_load_dword v21, v[10:11], off
	v_add_co_u32_e32 v10, vcc, s5, v8
	s_mov_b32 s5, 0x18000
	s_nop 0
	v_addc_co_u32_e32 v11, vcc, 0, v9, vcc
	global_load_dword v22, v[10:11], off
	v_add_co_u32_e32 v10, vcc, s5, v8
	s_mov_b32 s5, 0x1a000
	s_nop 0
	v_addc_co_u32_e32 v11, vcc, 0, v9, vcc
	global_load_dword v23, v[10:11], off
	v_add_co_u32_e32 v10, vcc, s5, v8
	s_mov_b32 s5, 0x1c000
	s_nop 0
	v_addc_co_u32_e32 v11, vcc, 0, v9, vcc
	global_load_dword v24, v[10:11], off
	v_add_co_u32_e32 v10, vcc, s5, v8
	s_mov_b32 s5, 0x1e000
	s_nop 0
	v_addc_co_u32_e32 v11, vcc, 0, v9, vcc
	global_load_dword v25, v[10:11], off
	v_add_co_u32_e32 v10, vcc, s5, v8
	s_mov_b32 s5, 0x20000
	s_nop 0
	v_addc_co_u32_e32 v11, vcc, 0, v9, vcc
	global_load_dword v26, v[10:11], off
	v_add_co_u32_e32 v10, vcc, s5, v8
	s_mov_b32 s5, 0x22000
	s_nop 0
	v_addc_co_u32_e32 v11, vcc, 0, v9, vcc
	global_load_dword v27, v[10:11], off
	v_add_co_u32_e32 v10, vcc, s5, v8
	s_mov_b32 s5, 0x24000
	s_nop 0
	v_addc_co_u32_e32 v11, vcc, 0, v9, vcc
	global_load_dword v28, v[10:11], off
	v_add_co_u32_e32 v10, vcc, s5, v8
	s_mov_b32 s5, 0x26000
	s_nop 0
	v_addc_co_u32_e32 v11, vcc, 0, v9, vcc
	global_load_dword v29, v[10:11], off
	v_add_co_u32_e32 v10, vcc, s5, v8
	s_mov_b32 s5, 0x28000
	s_nop 0
	v_addc_co_u32_e32 v11, vcc, 0, v9, vcc
	global_load_dword v104, v[10:11], off
	v_add_co_u32_e32 v10, vcc, s5, v8
	s_mov_b32 s5, 0x2a000
	s_nop 0
	v_addc_co_u32_e32 v11, vcc, 0, v9, vcc
	global_load_dword v105, v[10:11], off
	v_add_co_u32_e32 v10, vcc, s5, v8
	s_mov_b32 s5, 0x2c000
	s_nop 0
	v_addc_co_u32_e32 v11, vcc, 0, v9, vcc
	global_load_dword v106, v[10:11], off
	v_add_co_u32_e32 v10, vcc, s5, v8
	s_mov_b32 s5, 0x2e000
	s_nop 0
	v_addc_co_u32_e32 v11, vcc, 0, v9, vcc
	global_load_dword v107, v[10:11], off
	v_add_co_u32_e32 v10, vcc, s5, v8
	s_mov_b32 s5, 0x30000
	s_nop 0
	v_addc_co_u32_e32 v11, vcc, 0, v9, vcc
	global_load_dword v108, v[10:11], off
	v_add_co_u32_e32 v10, vcc, s5, v8
	s_mov_b32 s5, 0x32000
	s_nop 0
	v_addc_co_u32_e32 v11, vcc, 0, v9, vcc
	global_load_dword v109, v[10:11], off
	v_add_co_u32_e32 v10, vcc, s5, v8
	s_mov_b32 s5, 0x34000
	s_nop 0
	v_addc_co_u32_e32 v11, vcc, 0, v9, vcc
	global_load_dword v110, v[10:11], off
	v_add_co_u32_e32 v10, vcc, s5, v8
	s_mov_b32 s5, 0x36000
	s_nop 0
	v_addc_co_u32_e32 v11, vcc, 0, v9, vcc
	global_load_dword v111, v[10:11], off
	v_add_co_u32_e32 v10, vcc, s5, v8
	s_mov_b32 s5, 0x38000
	s_nop 0
	v_addc_co_u32_e32 v11, vcc, 0, v9, vcc
	global_load_dword v112, v[10:11], off
	v_add_co_u32_e32 v10, vcc, s5, v8
	s_mov_b32 s5, 0x3a000
	s_nop 0
	v_addc_co_u32_e32 v11, vcc, 0, v9, vcc
	global_load_dword v113, v[10:11], off
	v_add_co_u32_e32 v10, vcc, s5, v8
	s_mov_b32 s5, 0x3c000
	s_nop 0
	v_addc_co_u32_e32 v11, vcc, 0, v9, vcc
	global_load_dword v114, v[10:11], off
	v_add_co_u32_e32 v10, vcc, s5, v8
	s_mov_b32 s5, 0x3e000
	s_nop 0
	v_addc_co_u32_e32 v11, vcc, 0, v9, vcc
	v_add_co_u32_e32 v8, vcc, s5, v8
	global_load_dword v10, v[10:11], off
	s_nop 0
	v_addc_co_u32_e32 v9, vcc, 0, v9, vcc
	global_load_dword v8, v[8:9], off
	s_waitcnt vmcnt(0)
; __device__ __forceinline__ unsigned pk2(float lo, float hi) { f32x2_t v = {lo, hi}; bf16x2_t b = __builtin_convertvector(v, bf16x2_t); return __builtin_bit_cast(unsigned, b); }
; __device__ __forceinline__ void conv_item(const float* W, int K, int N, int kind, int item, const float* gain, unsigned char* Wb, float* scr, int lane) {
;     ...
; #pragma unroll
;     for (int i = 0; i < 32; ++i) scr[(2 * i + (lane >> 5)) * 33 + (lane & 31)] = wv_[i];
;     __builtin_amdgcn_s_waitcnt(0); asm volatile("" ::: "memory");
;     const int c = lane & 7; float gg[8];
; #pragma unroll
;     for (int e = 0; e < 8; ++e) gg[e] = gain ? gain[k0 + 8 * c + e] : 1.0f;
; #pragma unroll
;     for (int j = 0; j < 4; ++j) { const int n = (lane >> 3) + 8 * j; const float* s = scr + (8 * c) * 33 + n;
;         u32x4 o; o.x = pk2(s[0] * gg[0], s[33] * gg[1]); o.y = pk2(s[2 * 33] * gg[2], s[3 * 33] * gg[3]); o.z = pk2(s[4 * 33] * gg[4], s[5 * 33] * gg[5]); o.w = pk2(s[6 * 33] * gg[6], s[7 * 33] * gg[7]);
;         *(u32x4*)(wdst(kind, n0 + n, Wb) + k0 + 8 * c) = o; }
;     __builtin_amdgcn_s_waitcnt(0); asm volatile("" ::: "memory");
	ds_write2_b32 v5, v0, v12 offset1:66
	ds_write2_b32 v5, v13, v14 offset0:132 offset1:198
	v_add_u32_e32 v0, 0x400, v5
	ds_write2_b32 v0, v15, v16 offset0:8 offset1:74
	ds_write2_b32 v0, v17, v18 offset0:140 offset1:206
	v_add_u32_e32 v0, 0x800, v5
	ds_write2_b32 v0, v19, v20 offset0:16 offset1:82
	ds_write2_b32 v0, v21, v22 offset0:148 offset1:214
	v_add_u32_e32 v0, 0xc00, v5
	ds_write2_b32 v0, v23, v24 offset0:24 offset1:90
	ds_write2_b32 v0, v25, v26 offset0:156 offset1:222
	v_add_u32_e32 v0, 0x1000, v5
	ds_write2_b32 v0, v27, v28 offset0:32 offset1:98
	ds_write2_b32 v0, v29, v104 offset0:164 offset1:230
	v_add_u32_e32 v0, 0x1400, v5
	ds_write2_b32 v0, v105, v106 offset0:40 offset1:106
	ds_write2_b32 v0, v107, v108 offset0:172 offset1:238
	v_add_u32_e32 v0, 0x1800, v5
	ds_write2_b32 v0, v109, v110 offset0:48 offset1:114
	ds_write2_b32 v0, v111, v112 offset0:180 offset1:246
	v_add_u32_e32 v0, 0x1c00, v5
	ds_write2_b32 v0, v113, v114 offset0:56 offset1:122
	ds_write2_b32 v0, v10, v8 offset0:188 offset1:254
	s_waitcnt vmcnt(0) expcnt(0) lgkmcnt(0)
	ds_read_b32 v8, v30
	ds_read_b32 v113, v30 offset:132
	ds_read_b32 v9, v30 offset:264
	ds_read_b32 v114, v30 offset:396
	ds_read_b32 v10, v30 offset:528
	ds_read_b32 v111, v30 offset:660
	ds_read_b32 v11, v30 offset:792
	ds_read_b32 v112, v30 offset:924
	s_lshl_b64 s[6:7], s[92:93], 1
	s_waitcnt lgkmcnt(0)
	v_cvt_pk_bf16_f32 v8, v8, v113
	v_cvt_pk_bf16_f32 v9, v9, v114
	v_cvt_pk_bf16_f32 v10, v10, v111
	v_cvt_pk_bf16_f32 v11, v11, v112
	v_add_u32_e32 v0, s4, v49
	v_add_u32_e32 v12, 0x60a00, v0
	v_ashrrev_i32_e32 v13, 31, v12
	v_lshlrev_b64 v[12:13], 10, v[12:13]
	v_lshl_add_u64 v[12:13], s[46:47], 0, v[12:13]
	v_lshl_add_u64 v[12:13], v[12:13], 0, s[6:7]
	v_lshlrev_b32_e32 v0, 1, v6
	v_lshl_add_u64 v[12:13], v[12:13], 0, v[0:1]
	flat_store_dwordx4 v[12:13], v[8:11]
	ds_read_b32 v8, v30 offset:32
	ds_read_b32 v113, v30 offset:164
	ds_read_b32 v9, v30 offset:296
	ds_read_b32 v114, v30 offset:428
	ds_read_b32 v10, v30 offset:560
	ds_read_b32 v111, v30 offset:692
	ds_read_b32 v11, v30 offset:824
	ds_read_b32 v112, v30 offset:956
	s_waitcnt lgkmcnt(0)
	v_cvt_pk_bf16_f32 v8, v8, v113
	v_cvt_pk_bf16_f32 v9, v9, v114
	v_cvt_pk_bf16_f32 v10, v10, v111
	v_cvt_pk_bf16_f32 v11, v11, v112
	v_add_u32_e32 v12, s4, v50
	v_add_u32_e32 v12, 0x60a00, v12
	v_ashrrev_i32_e32 v13, 31, v12
	v_lshlrev_b64 v[12:13], 10, v[12:13]
	v_lshl_add_u64 v[12:13], s[46:47], 0, v[12:13]
	v_lshl_add_u64 v[12:13], v[12:13], 0, s[6:7]
	v_lshl_add_u64 v[12:13], v[12:13], 0, v[0:1]
	flat_store_dwordx4 v[12:13], v[8:11]
	ds_read_b32 v8, v30 offset:64
	ds_read_b32 v113, v30 offset:196
	ds_read_b32 v9, v30 offset:328
	ds_read_b32 v114, v30 offset:460
	ds_read_b32 v10, v30 offset:592
	ds_read_b32 v111, v30 offset:724
	ds_read_b32 v11, v30 offset:856
	ds_read_b32 v112, v30 offset:988
	s_waitcnt lgkmcnt(0)
	v_cvt_pk_bf16_f32 v8, v8, v113
	v_cvt_pk_bf16_f32 v9, v9, v114
	v_cvt_pk_bf16_f32 v10, v10, v111
	v_cvt_pk_bf16_f32 v11, v11, v112
	v_add_u32_e32 v12, s4, v51
	v_add_u32_e32 v12, 0x60a00, v12
	v_ashrrev_i32_e32 v13, 31, v12
	v_lshlrev_b64 v[12:13], 10, v[12:13]
	v_lshl_add_u64 v[12:13], s[46:47], 0, v[12:13]
	v_lshl_add_u64 v[12:13], v[12:13], 0, s[6:7]
	v_lshl_add_u64 v[12:13], v[12:13], 0, v[0:1]
	flat_store_dwordx4 v[12:13], v[8:11]
	ds_read_b32 v10, v30 offset:96
	ds_read_b32 v11, v30 offset:228
	ds_read_b32 v14, v30 offset:360
	ds_read_b32 v15, v30 offset:492
	ds_read_b32 v16, v30 offset:624
	ds_read_b32 v17, v30 offset:756
	ds_read_b32 v18, v30 offset:888
	ds_read_b32 v19, v30 offset:1020
	v_add_u32_e32 v8, s4, v52
	v_add_u32_e32 v8, 0x60a00, v8
	v_ashrrev_i32_e32 v9, 31, v8
	v_lshlrev_b64 v[8:9], 10, v[8:9]
	v_lshl_add_u64 v[12:13], s[46:47], 0, v[8:9]
	v_lshl_add_u64 v[12:13], v[12:13], 0, s[6:7]
	s_waitcnt lgkmcnt(0)
	v_cvt_pk_bf16_f32 v8, v10, v11
	v_cvt_pk_bf16_f32 v9, v14, v15
	v_cvt_pk_bf16_f32 v10, v16, v17
	v_cvt_pk_bf16_f32 v11, v18, v19
	v_lshl_add_u64 v[12:13], v[12:13], 0, v[0:1]
	flat_store_dwordx4 v[12:13], v[8:11]
	s_waitcnt lgkmcnt(0)

; __device__ __forceinline__ void conv_item(const float* W, int K, int N, int kind, int item, const float* gain, unsigned char* Wb, float* scr, int lane) {
;     const int nblk = N / 32, kb = item / nblk, nb = item - kb * nblk, k0 = 64 * kb, n0 = 32 * nb;
;     float wv_[32];
; #pragma unroll
;     for (int i = 0; i < 32; ++i) wv_[i] = W[(size_t)(k0 + 2 * i + (lane >> 5)) * N + n0 + (lane & 31)];
; __global__ void __launch_bounds__(512, 2) mk_fwd(Args a) {
;     ...
;                     if (r < 256) { conv_item(ap->in[13] + L * 512 * 1024, 512, 1024, 8, r, nullptr, Wb, scr, lane); continue; } r -= 256;
.LBB0_306:
	s_andn2_b64 vcc, exec, s[4:5]
	s_cbranch_vccnz .LBB0_308
	s_lshl_b32 s4, s77, 5
	s_and_b32 s6, s4, 0xfffffc00
	v_readlane_b32 s4, v254, 40
	v_readlane_b32 s5, v254, 41
	s_load_dwordx2 s[4:5], s[4:5], 0x68
	s_lshl_b32 s7, s73, 1
	v_lshlrev_b32_e32 v0, 2, v4
	s_waitcnt lgkmcnt(0)
	s_add_u32 s12, s4, s44
	s_addc_u32 s13, s5, s45
	s_add_i32 s4, s7, 0x4c0
	s_and_b32 s92, s4, 0xffffffc0
	s_sub_i32 s4, s75, s6
	s_add_i32 s4, s4, 0xfffa1600
	s_ashr_i32 s5, s4, 31
	s_lshl_b64 s[6:7], s[4:5], 2
	s_add_u32 s6, s12, s6
	v_or_b32_e32 v10, s92, v3
	s_addc_u32 s7, s13, s7
	v_lshl_add_u64 v[8:9], s[6:7], 0, v[0:1]
	v_lshlrev_b32_e32 v0, 10, v10
	v_lshl_add_u64 v[8:9], v[0:1], 2, v[8:9]
	s_movk_i32 s5, 0x2000
	v_add_co_u32_e32 v10, vcc, s5, v8
	s_movk_i32 s5, 0x4000
	s_nop 0
	v_addc_co_u32_e32 v11, vcc, 0, v9, vcc
	global_load_dword v0, v[8:9], off
	global_load_dword v12, v[10:11], off
	v_add_co_u32_e32 v10, vcc, s5, v8
	s_movk_i32 s5, 0x6000
	s_nop 0
	v_addc_co_u32_e32 v11, vcc, 0, v9, vcc
	global_load_dword v13, v[10:11], off
	v_add_co_u32_e32 v10, vcc, s5, v8
	s_mov_b32 s5, 0x8000
	s_nop 0
	v_addc_co_u32_e32 v11, vcc, 0, v9, vcc
	global_load_dword v14, v[10:11], off
	v_add_co_u32_e32 v10, vcc, s5, v8
	s_mov_b32 s5, 0xa000
	s_nop 0
	v_addc_co_u32_e32 v11, vcc, 0, v9, vcc
	global_load_dword v15, v[10:11], off
	v_add_co_u32_e32 v10, vcc, s5, v8
	s_mov_b32 s5, 0xc000
	s_nop 0
	v_addc_co_u32_e32 v11, vcc, 0, v9, vcc
	global_load_dword v16, v[10:11], off
	v_add_co_u32_e32 v10, vcc, s5, v8
	s_mov_b32 s5, 0xe000
	s_nop 0
	v_addc_co_u32_e32 v11, vcc, 0, v9, vcc
	global_load_dword v17, v[10:11], off
	v_add_co_u32_e32 v10, vcc, s5, v8
	s_mov_b32 s5, 0x10000
	s_nop 0
	v_addc_co_u32_e32 v11, vcc, 0, v9, vcc
	global_load_dword v18, v[10:11], off
	v_add_co_u32_e32 v10, vcc, s5, v8
	s_mov_b32 s5, 0x12000
	s_nop 0
	v_addc_co_u32_e32 v11, vcc, 0, v9, vcc
	global_load_dword v19, v[10:11], off
	v_add_co_u32_e32 v10, vcc, s5, v8
	s_mov_b32 s5, 0x14000
	s_nop 0
	v_addc_co_u32_e32 v11, vcc, 0, v9, vcc
	global_load_dword v20, v[10:11], off
	v_add_co_u32_e32 v10, vcc, s5, v8
	s_mov_b32 s5, 0x16000
	s_nop 0
	v_addc_co_u32_e32 v11, vcc, 0, v9, vcc
	global_load_dword v21, v[10:11], off
	v_add_co_u32_e32 v10, vcc, s5, v8
	s_mov_b32 s5, 0x18000
	s_nop 0
	v_addc_co_u32_e32 v11, vcc, 0, v9, vcc
	global_load_dword v22, v[10:11], off
	v_add_co_u32_e32 v10, vcc, s5, v8
	s_mov_b32 s5, 0x1a000
	s_nop 0
	v_addc_co_u32_e32 v11, vcc, 0, v9, vcc
	global_load_dword v23, v[10:11], off
	v_add_co_u32_e32 v10, vcc, s5, v8
	s_mov_b32 s5, 0x1c000
	s_nop 0
	v_addc_co_u32_e32 v11, vcc, 0, v9, vcc
	global_load_dword v24, v[10:11], off
	v_add_co_u32_e32 v10, vcc, s5, v8
	s_mov_b32 s5, 0x1e000
	s_nop 0
	v_addc_co_u32_e32 v11, vcc, 0, v9, vcc
	global_load_dword v25, v[10:11], off
	v_add_co_u32_e32 v10, vcc, s5, v8
	s_mov_b32 s5, 0x20000
	s_nop 0
	v_addc_co_u32_e32 v11, vcc, 0, v9, vcc
	global_load_dword v26, v[10:11], off
	v_add_co_u32_e32 v10, vcc, s5, v8
	s_mov_b32 s5, 0x22000
	s_nop 0
	v_addc_co_u32_e32 v11, vcc, 0, v9, vcc
	global_load_dword v27, v[10:11], off
	v_add_co_u32_e32 v10, vcc, s5, v8
	s_mov_b32 s5, 0x24000
	s_nop 0
	v_addc_co_u32_e32 v11, vcc, 0, v9, vcc
	global_load_dword v28, v[10:11], off
	v_add_co_u32_e32 v10, vcc, s5, v8
	s_mov_b32 s5, 0x26000
	s_nop 0
	v_addc_co_u32_e32 v11, vcc, 0, v9, vcc
	global_load_dword v29, v[10:11], off
	v_add_co_u32_e32 v10, vcc, s5, v8
	s_mov_b32 s5, 0x28000
	s_nop 0
	v_addc_co_u32_e32 v11, vcc, 0, v9, vcc
	global_load_dword v104, v[10:11], off
	v_add_co_u32_e32 v10, vcc, s5, v8
	s_mov_b32 s5, 0x2a000
	s_nop 0
	v_addc_co_u32_e32 v11, vcc, 0, v9, vcc
	global_load_dword v105, v[10:11], off
	v_add_co_u32_e32 v10, vcc, s5, v8
	s_mov_b32 s5, 0x2c000
	s_nop 0
	v_addc_co_u32_e32 v11, vcc, 0, v9, vcc
	global_load_dword v106, v[10:11], off
	v_add_co_u32_e32 v10, vcc, s5, v8
	s_mov_b32 s5, 0x2e000
	s_nop 0
	v_addc_co_u32_e32 v11, vcc, 0, v9, vcc
	global_load_dword v107, v[10:11], off
	v_add_co_u32_e32 v10, vcc, s5, v8
	s_mov_b32 s5, 0x30000
	s_nop 0
	v_addc_co_u32_e32 v11, vcc, 0, v9, vcc
	global_load_dword v108, v[10:11], off
	v_add_co_u32_e32 v10, vcc, s5, v8
	s_mov_b32 s5, 0x32000
	s_nop 0
	v_addc_co_u32_e32 v11, vcc, 0, v9, vcc
	global_load_dword v109, v[10:11], off
	v_add_co_u32_e32 v10, vcc, s5, v8
	s_mov_b32 s5, 0x34000
	s_nop 0
	v_addc_co_u32_e32 v11, vcc, 0, v9, vcc
	global_load_dword v110, v[10:11], off
	v_add_co_u32_e32 v10, vcc, s5, v8
	s_mov_b32 s5, 0x36000
	s_nop 0
	v_addc_co_u32_e32 v11, vcc, 0, v9, vcc
	global_load_dword v111, v[10:11], off
	v_add_co_u32_e32 v10, vcc, s5, v8
	s_mov_b32 s5, 0x38000
	s_nop 0
	v_addc_co_u32_e32 v11, vcc, 0, v9, vcc
	global_load_dword v112, v[10:11], off
	v_add_co_u32_e32 v10, vcc, s5, v8
	s_mov_b32 s5, 0x3a000
	s_nop 0
	v_addc_co_u32_e32 v11, vcc, 0, v9, vcc
	global_load_dword v113, v[10:11], off
	v_add_co_u32_e32 v10, vcc, s5, v8
	s_mov_b32 s5, 0x3c000
	s_nop 0
	v_addc_co_u32_e32 v11, vcc, 0, v9, vcc
	global_load_dword v114, v[10:11], off
	v_add_co_u32_e32 v10, vcc, s5, v8
	s_mov_b32 s5, 0x3e000
	s_nop 0
	v_addc_co_u32_e32 v11, vcc, 0, v9, vcc
	v_add_co_u32_e32 v8, vcc, s5, v8
	global_load_dword v10, v[10:11], off
	s_nop 0
	v_addc_co_u32_e32 v9, vcc, 0, v9, vcc
	global_load_dword v8, v[8:9], off
	s_waitcnt vmcnt(0)
; __device__ __forceinline__ unsigned pk2(float lo, float hi) { f32x2_t v = {lo, hi}; bf16x2_t b = __builtin_convertvector(v, bf16x2_t); return __builtin_bit_cast(unsigned, b); }
; __device__ __forceinline__ void conv_item(const float* W, int K, int N, int kind, int item, const float* gain, unsigned char* Wb, float* scr, int lane) {
;     ...
; #pragma unroll
;     for (int i = 0; i < 32; ++i) scr[(2 * i + (lane >> 5)) * 33 + (lane & 31)] = wv_[i];
;     __builtin_amdgcn_s_waitcnt(0); asm volatile("" ::: "memory");
;     const int c = lane & 7; float gg[8];
; #pragma unroll
;     for (int e = 0; e < 8; ++e) gg[e] = gain ? gain[k0 + 8 * c + e] : 1.0f;
; #pragma unroll
;     for (int j = 0; j < 4; ++j) { const int n = (lane >> 3) + 8 * j; const float* s = scr + (8 * c) * 33 + n;
;         u32x4 o; o.x = pk2(s[0] * gg[0], s[33] * gg[1]); o.y = pk2(s[2 * 33] * gg[2], s[3 * 33] * gg[3]); o.z = pk2(s[4 * 33] * gg[4], s[5 * 33] * gg[5]); o.w = pk2(s[6 * 33] * gg[6], s[7 * 33] * gg[7]);
;         *(u32x4*)(wdst(kind, n0 + n, Wb) + k0 + 8 * c) = o; }
;     __builtin_amdgcn_s_waitcnt(0); asm volatile("" ::: "memory");
	ds_write2_b32 v5, v0, v12 offset1:66
	ds_write2_b32 v5, v13, v14 offset0:132 offset1:198
	v_add_u32_e32 v0, 0x400, v5
	ds_write2_b32 v0, v15, v16 offset0:8 offset1:74
	ds_write2_b32 v0, v17, v18 offset0:140 offset1:206
	v_add_u32_e32 v0, 0x800, v5
	ds_write2_b32 v0, v19, v20 offset0:16 offset1:82
	ds_write2_b32 v0, v21, v22 offset0:148 offset1:214
	v_add_u32_e32 v0, 0xc00, v5
	ds_write2_b32 v0, v23, v24 offset0:24 offset1:90
	ds_write2_b32 v0, v25, v26 offset0:156 offset1:222
	v_add_u32_e32 v0, 0x1000, v5
	ds_write2_b32 v0, v27, v28 offset0:32 offset1:98
	ds_write2_b32 v0, v29, v104 offset0:164 offset1:230
	v_add_u32_e32 v0, 0x1400, v5
	ds_write2_b32 v0, v105, v106 offset0:40 offset1:106
	ds_write2_b32 v0, v107, v108 offset0:172 offset1:238
	v_add_u32_e32 v0, 0x1800, v5
	ds_write2_b32 v0, v109, v110 offset0:48 offset1:114
	ds_write2_b32 v0, v111, v112 offset0:180 offset1:246
	v_add_u32_e32 v0, 0x1c00, v5
	ds_write2_b32 v0, v113, v114 offset0:56 offset1:122
	ds_write2_b32 v0, v10, v8 offset0:188 offset1:254
	s_waitcnt vmcnt(0) expcnt(0) lgkmcnt(0)
	ds_read_b32 v8, v30
	ds_read_b32 v113, v30 offset:132
	ds_read_b32 v9, v30 offset:264
	ds_read_b32 v114, v30 offset:396
	ds_read_b32 v10, v30 offset:528
	ds_read_b32 v111, v30 offset:660
	ds_read_b32 v11, v30 offset:792
	ds_read_b32 v112, v30 offset:924
	s_lshl_b64 s[6:7], s[92:93], 1
	s_waitcnt lgkmcnt(0)
	v_cvt_pk_bf16_f32 v8, v8, v113
	v_cvt_pk_bf16_f32 v9, v9, v114
	v_cvt_pk_bf16_f32 v10, v10, v111
	v_cvt_pk_bf16_f32 v11, v11, v112
	v_add_u32_e32 v0, s4, v53
	v_add_u32_e32 v12, 0x5ea00, v0
	v_ashrrev_i32_e32 v13, 31, v12
	v_lshlrev_b64 v[12:13], 10, v[12:13]
	v_lshl_add_u64 v[12:13], s[48:49], 0, v[12:13]
	v_lshl_add_u64 v[12:13], v[12:13], 0, s[6:7]
	v_lshlrev_b32_e32 v0, 1, v6
	v_lshl_add_u64 v[12:13], v[12:13], 0, v[0:1]
	flat_store_dwordx4 v[12:13], v[8:11]
	ds_read_b32 v8, v30 offset:32
	ds_read_b32 v113, v30 offset:164
	ds_read_b32 v9, v30 offset:296
	ds_read_b32 v114, v30 offset:428
	ds_read_b32 v10, v30 offset:560
	ds_read_b32 v111, v30 offset:692
	ds_read_b32 v11, v30 offset:824
	ds_read_b32 v112, v30 offset:956
	s_waitcnt lgkmcnt(0)
	v_cvt_pk_bf16_f32 v8, v8, v113
	v_cvt_pk_bf16_f32 v9, v9, v114
	v_cvt_pk_bf16_f32 v10, v10, v111
	v_cvt_pk_bf16_f32 v11, v11, v112
	v_add_u32_e32 v12, s4, v54
	v_add_u32_e32 v12, 0x5ea00, v12
	v_ashrrev_i32_e32 v13, 31, v12
	v_lshlrev_b64 v[12:13], 10, v[12:13]
	v_lshl_add_u64 v[12:13], s[48:49], 0, v[12:13]
	v_lshl_add_u64 v[12:13], v[12:13], 0, s[6:7]
	v_lshl_add_u64 v[12:13], v[12:13], 0, v[0:1]
	flat_store_dwordx4 v[12:13], v[8:11]
	ds_read_b32 v8, v30 offset:64
	ds_read_b32 v113, v30 offset:196
	ds_read_b32 v9, v30 offset:328
	ds_read_b32 v114, v30 offset:460
	ds_read_b32 v10, v30 offset:592
	ds_read_b32 v111, v30 offset:724
	ds_read_b32 v11, v30 offset:856
	ds_read_b32 v112, v30 offset:988
	s_waitcnt lgkmcnt(0)
	v_cvt_pk_bf16_f32 v8, v8, v113
	v_cvt_pk_bf16_f32 v9, v9, v114
	v_cvt_pk_bf16_f32 v10, v10, v111
	v_cvt_pk_bf16_f32 v11, v11, v112
	v_add_u32_e32 v12, s4, v55
	v_add_u32_e32 v12, 0x5ea00, v12
	v_ashrrev_i32_e32 v13, 31, v12
	v_lshlrev_b64 v[12:13], 10, v[12:13]
	v_lshl_add_u64 v[12:13], s[48:49], 0, v[12:13]
	v_lshl_add_u64 v[12:13], v[12:13], 0, s[6:7]
	v_lshl_add_u64 v[12:13], v[12:13], 0, v[0:1]
	flat_store_dwordx4 v[12:13], v[8:11]
	ds_read_b32 v10, v30 offset:96
	ds_read_b32 v11, v30 offset:228
	ds_read_b32 v14, v30 offset:360
	ds_read_b32 v15, v30 offset:492
	ds_read_b32 v16, v30 offset:624
	ds_read_b32 v17, v30 offset:756
	ds_read_b32 v18, v30 offset:888
	ds_read_b32 v19, v30 offset:1020
	v_add_u32_e32 v8, s4, v56
	v_add_u32_e32 v8, 0x5ea00, v8
	v_ashrrev_i32_e32 v9, 31, v8
	v_lshlrev_b64 v[8:9], 10, v[8:9]
	v_lshl_add_u64 v[12:13], s[48:49], 0, v[8:9]
	v_lshl_add_u64 v[12:13], v[12:13], 0, s[6:7]
	s_waitcnt lgkmcnt(0)
	v_cvt_pk_bf16_f32 v8, v10, v11
	v_cvt_pk_bf16_f32 v9, v14, v15
	v_cvt_pk_bf16_f32 v10, v16, v17
	v_cvt_pk_bf16_f32 v11, v18, v19
	v_lshl_add_u64 v[12:13], v[12:13], 0, v[0:1]
	flat_store_dwordx4 v[12:13], v[8:11]
	s_waitcnt lgkmcnt(0)

; __device__ __forceinline__ void conv_item(const float* W, int K, int N, int kind, int item, const float* gain, unsigned char* Wb, float* scr, int lane) {
;     const int nblk = N / 32, kb = item / nblk, nb = item - kb * nblk, k0 = 64 * kb, n0 = 32 * nb;
;     float wv_[32];
; #pragma unroll
;     for (int i = 0; i < 32; ++i) wv_[i] = W[(size_t)(k0 + 2 * i + (lane >> 5)) * N + n0 + (lane & 31)];
; __global__ void __launch_bounds__(512, 2) mk_fwd(Args a) {
;     ...
;                     if (r < 256) { conv_item(ap->in[11] + L * 512 * 1024, 512, 1024, 7, r, nullptr, Wb, scr, lane); continue; } r -= 256;
.LBB0_309:
	s_andn2_b64 vcc, exec, s[4:5]
	s_cbranch_vccnz .LBB0_311
	s_lshl_b32 s4, s78, 5
	s_and_b32 s6, s4, 0xfffffc00
	v_readlane_b32 s4, v254, 40
	v_readlane_b32 s5, v254, 41
	s_load_dwordx2 s[4:5], s[4:5], 0x58
	s_lshl_b32 s7, s73, 1
	v_lshlrev_b32_e32 v0, 2, v4
	s_waitcnt lgkmcnt(0)
	s_add_u32 s12, s4, s44
	s_addc_u32 s13, s5, s45
	s_add_i32 s4, s7, 0x6c0
	s_and_b32 s92, s4, 0xffffffc0
	s_sub_i32 s4, s75, s6
	s_add_i32 s4, s4, 0xfffa3600
	s_ashr_i32 s5, s4, 31
	s_lshl_b64 s[6:7], s[4:5], 2
	s_add_u32 s6, s12, s6
	v_or_b32_e32 v10, s92, v3
	s_addc_u32 s7, s13, s7
	v_lshl_add_u64 v[8:9], s[6:7], 0, v[0:1]
	v_lshlrev_b32_e32 v0, 10, v10
	v_lshl_add_u64 v[8:9], v[0:1], 2, v[8:9]
	s_movk_i32 s5, 0x2000
	v_add_co_u32_e32 v10, vcc, s5, v8
	s_movk_i32 s5, 0x4000
	s_nop 0
	v_addc_co_u32_e32 v11, vcc, 0, v9, vcc
	global_load_dword v0, v[8:9], off
	global_load_dword v12, v[10:11], off
	v_add_co_u32_e32 v10, vcc, s5, v8
	s_movk_i32 s5, 0x6000
	s_nop 0
	v_addc_co_u32_e32 v11, vcc, 0, v9, vcc
	global_load_dword v13, v[10:11], off
	v_add_co_u32_e32 v10, vcc, s5, v8
	s_mov_b32 s5, 0x8000
	s_nop 0
	v_addc_co_u32_e32 v11, vcc, 0, v9, vcc
	global_load_dword v14, v[10:11], off
	v_add_co_u32_e32 v10, vcc, s5, v8
	s_mov_b32 s5, 0xa000
	s_nop 0
	v_addc_co_u32_e32 v11, vcc, 0, v9, vcc
	global_load_dword v15, v[10:11], off
	v_add_co_u32_e32 v10, vcc, s5, v8
	s_mov_b32 s5, 0xc000
	s_nop 0
	v_addc_co_u32_e32 v11, vcc, 0, v9, vcc
	global_load_dword v16, v[10:11], off
	v_add_co_u32_e32 v10, vcc, s5, v8
	s_mov_b32 s5, 0xe000
	s_nop 0
	v_addc_co_u32_e32 v11, vcc, 0, v9, vcc
	global_load_dword v17, v[10:11], off
	v_add_co_u32_e32 v10, vcc, s5, v8
	s_mov_b32 s5, 0x10000
	s_nop 0
	v_addc_co_u32_e32 v11, vcc, 0, v9, vcc
	global_load_dword v18, v[10:11], off
	v_add_co_u32_e32 v10, vcc, s5, v8
	s_mov_b32 s5, 0x12000
	s_nop 0
	v_addc_co_u32_e32 v11, vcc, 0, v9, vcc
	global_load_dword v19, v[10:11], off
	v_add_co_u32_e32 v10, vcc, s5, v8
	s_mov_b32 s5, 0x14000
	s_nop 0
	v_addc_co_u32_e32 v11, vcc, 0, v9, vcc
	global_load_dword v20, v[10:11], off
	v_add_co_u32_e32 v10, vcc, s5, v8
	s_mov_b32 s5, 0x16000
	s_nop 0
	v_addc_co_u32_e32 v11, vcc, 0, v9, vcc
	global_load_dword v21, v[10:11], off
	v_add_co_u32_e32 v10, vcc, s5, v8
	s_mov_b32 s5, 0x18000
	s_nop 0
	v_addc_co_u32_e32 v11, vcc, 0, v9, vcc
	global_load_dword v22, v[10:11], off
	v_add_co_u32_e32 v10, vcc, s5, v8
	s_mov_b32 s5, 0x1a000
	s_nop 0
	v_addc_co_u32_e32 v11, vcc, 0, v9, vcc
	global_load_dword v23, v[10:11], off
	v_add_co_u32_e32 v10, vcc, s5, v8
	s_mov_b32 s5, 0x1c000
	s_nop 0
	v_addc_co_u32_e32 v11, vcc, 0, v9, vcc
	global_load_dword v24, v[10:11], off
	v_add_co_u32_e32 v10, vcc, s5, v8
	s_mov_b32 s5, 0x1e000
	s_nop 0
	v_addc_co_u32_e32 v11, vcc, 0, v9, vcc
	global_load_dword v25, v[10:11], off
	v_add_co_u32_e32 v10, vcc, s5, v8
	s_mov_b32 s5, 0x20000
	s_nop 0
	v_addc_co_u32_e32 v11, vcc, 0, v9, vcc
	global_load_dword v26, v[10:11], off
	v_add_co_u32_e32 v10, vcc, s5, v8
	s_mov_b32 s5, 0x22000
	s_nop 0
	v_addc_co_u32_e32 v11, vcc, 0, v9, vcc
	global_load_dword v27, v[10:11], off
	v_add_co_u32_e32 v10, vcc, s5, v8
	s_mov_b32 s5, 0x24000
	s_nop 0
	v_addc_co_u32_e32 v11, vcc, 0, v9, vcc
	global_load_dword v28, v[10:11], off
	v_add_co_u32_e32 v10, vcc, s5, v8
	s_mov_b32 s5, 0x26000
	s_nop 0
	v_addc_co_u32_e32 v11, vcc, 0, v9, vcc
	global_load_dword v29, v[10:11], off
	v_add_co_u32_e32 v10, vcc, s5, v8
	s_mov_b32 s5, 0x28000
	s_nop 0
	v_addc_co_u32_e32 v11, vcc, 0, v9, vcc
	global_load_dword v104, v[10:11], off
	v_add_co_u32_e32 v10, vcc, s5, v8
	s_mov_b32 s5, 0x2a000
	s_nop 0
	v_addc_co_u32_e32 v11, vcc, 0, v9, vcc
	global_load_dword v105, v[10:11], off
	v_add_co_u32_e32 v10, vcc, s5, v8
	s_mov_b32 s5, 0x2c000
	s_nop 0
	v_addc_co_u32_e32 v11, vcc, 0, v9, vcc
	global_load_dword v106, v[10:11], off
	v_add_co_u32_e32 v10, vcc, s5, v8
	s_mov_b32 s5, 0x2e000
	s_nop 0
	v_addc_co_u32_e32 v11, vcc, 0, v9, vcc
	global_load_dword v107, v[10:11], off
	v_add_co_u32_e32 v10, vcc, s5, v8
	s_mov_b32 s5, 0x30000
	s_nop 0
	v_addc_co_u32_e32 v11, vcc, 0, v9, vcc
	global_load_dword v108, v[10:11], off
	v_add_co_u32_e32 v10, vcc, s5, v8
	s_mov_b32 s5, 0x32000
	s_nop 0
	v_addc_co_u32_e32 v11, vcc, 0, v9, vcc
	global_load_dword v109, v[10:11], off
	v_add_co_u32_e32 v10, vcc, s5, v8
	s_mov_b32 s5, 0x34000
	s_nop 0
	v_addc_co_u32_e32 v11, vcc, 0, v9, vcc
	global_load_dword v110, v[10:11], off
	v_add_co_u32_e32 v10, vcc, s5, v8
	s_mov_b32 s5, 0x36000
	s_nop 0
	v_addc_co_u32_e32 v11, vcc, 0, v9, vcc
	global_load_dword v111, v[10:11], off
	v_add_co_u32_e32 v10, vcc, s5, v8
	s_mov_b32 s5, 0x38000
	s_nop 0
	v_addc_co_u32_e32 v11, vcc, 0, v9, vcc
	global_load_dword v112, v[10:11], off
	v_add_co_u32_e32 v10, vcc, s5, v8
	s_mov_b32 s5, 0x3a000
	s_nop 0
	v_addc_co_u32_e32 v11, vcc, 0, v9, vcc
	global_load_dword v113, v[10:11], off
	v_add_co_u32_e32 v10, vcc, s5, v8
	s_mov_b32 s5, 0x3c000
	s_nop 0
	v_addc_co_u32_e32 v11, vcc, 0, v9, vcc
	global_load_dword v114, v[10:11], off
	v_add_co_u32_e32 v10, vcc, s5, v8
	s_mov_b32 s5, 0x3e000
	s_nop 0
	v_addc_co_u32_e32 v11, vcc, 0, v9, vcc
	v_add_co_u32_e32 v8, vcc, s5, v8
	global_load_dword v10, v[10:11], off
	s_nop 0
	v_addc_co_u32_e32 v9, vcc, 0, v9, vcc
	global_load_dword v8, v[8:9], off
	s_waitcnt vmcnt(0)
; __device__ __forceinline__ unsigned pk2(float lo, float hi) { f32x2_t v = {lo, hi}; bf16x2_t b = __builtin_convertvector(v, bf16x2_t); return __builtin_bit_cast(unsigned, b); }
; __device__ __forceinline__ void conv_item(const float* W, int K, int N, int kind, int item, const float* gain, unsigned char* Wb, float* scr, int lane) {
;     ...
; #pragma unroll
;     for (int i = 0; i < 32; ++i) scr[(2 * i + (lane >> 5)) * 33 + (lane & 31)] = wv_[i];
;     __builtin_amdgcn_s_waitcnt(0); asm volatile("" ::: "memory");
;     const int c = lane & 7; float gg[8];
; #pragma unroll
;     for (int e = 0; e < 8; ++e) gg[e] = gain ? gain[k0 + 8 * c + e] : 1.0f;
; #pragma unroll
;     for (int j = 0; j < 4; ++j) { const int n = (lane >> 3) + 8 * j; const float* s = scr + (8 * c) * 33 + n;
;         u32x4 o; o.x = pk2(s[0] * gg[0], s[33] * gg[1]); o.y = pk2(s[2 * 33] * gg[2], s[3 * 33] * gg[3]); o.z = pk2(s[4 * 33] * gg[4], s[5 * 33] * gg[5]); o.w = pk2(s[6 * 33] * gg[6], s[7 * 33] * gg[7]);
;         *(u32x4*)(wdst(kind, n0 + n, Wb) + k0 + 8 * c) = o; }
;     __builtin_amdgcn_s_waitcnt(0); asm volatile("" ::: "memory");
	ds_write2_b32 v5, v0, v12 offset1:66
	ds_write2_b32 v5, v13, v14 offset0:132 offset1:198
	v_add_u32_e32 v0, 0x400, v5
	ds_write2_b32 v0, v15, v16 offset0:8 offset1:74
	ds_write2_b32 v0, v17, v18 offset0:140 offset1:206
	v_add_u32_e32 v0, 0x800, v5
	ds_write2_b32 v0, v19, v20 offset0:16 offset1:82
	ds_write2_b32 v0, v21, v22 offset0:148 offset1:214
	v_add_u32_e32 v0, 0xc00, v5
	ds_write2_b32 v0, v23, v24 offset0:24 offset1:90
	ds_write2_b32 v0, v25, v26 offset0:156 offset1:222
	v_add_u32_e32 v0, 0x1000, v5
	ds_write2_b32 v0, v27, v28 offset0:32 offset1:98
	ds_write2_b32 v0, v29, v104 offset0:164 offset1:230
	v_add_u32_e32 v0, 0x1400, v5
	ds_write2_b32 v0, v105, v106 offset0:40 offset1:106
	ds_write2_b32 v0, v107, v108 offset0:172 offset1:238
	v_add_u32_e32 v0, 0x1800, v5
	ds_write2_b32 v0, v109, v110 offset0:48 offset1:114
	ds_write2_b32 v0, v111, v112 offset0:180 offset1:246
	v_add_u32_e32 v0, 0x1c00, v5
	ds_write2_b32 v0, v113, v114 offset0:56 offset1:122
	ds_write2_b32 v0, v10, v8 offset0:188 offset1:254
	s_waitcnt vmcnt(0) expcnt(0) lgkmcnt(0)
	ds_read_b32 v8, v30
	ds_read_b32 v113, v30 offset:132
	ds_read_b32 v9, v30 offset:264
	ds_read_b32 v114, v30 offset:396
	ds_read_b32 v10, v30 offset:528
	ds_read_b32 v111, v30 offset:660
	ds_read_b32 v11, v30 offset:792
	ds_read_b32 v112, v30 offset:924
	s_lshl_b64 s[6:7], s[92:93], 1
	s_waitcnt lgkmcnt(0)
	v_cvt_pk_bf16_f32 v8, v8, v113
	v_cvt_pk_bf16_f32 v9, v9, v114
	v_cvt_pk_bf16_f32 v10, v10, v111
	v_cvt_pk_bf16_f32 v11, v11, v112
	v_add_u32_e32 v0, s4, v57
	v_add_u32_e32 v12, 0x5ca00, v0
	v_ashrrev_i32_e32 v13, 31, v12
	v_lshlrev_b64 v[12:13], 10, v[12:13]
	v_lshl_add_u64 v[12:13], s[50:51], 0, v[12:13]
	v_lshl_add_u64 v[12:13], v[12:13], 0, s[6:7]
	v_lshlrev_b32_e32 v0, 1, v6
	v_lshl_add_u64 v[12:13], v[12:13], 0, v[0:1]
	flat_store_dwordx4 v[12:13], v[8:11]
	ds_read_b32 v8, v30 offset:32
	ds_read_b32 v113, v30 offset:164
	ds_read_b32 v9, v30 offset:296
	ds_read_b32 v114, v30 offset:428
	ds_read_b32 v10, v30 offset:560
	ds_read_b32 v111, v30 offset:692
	ds_read_b32 v11, v30 offset:824
	ds_read_b32 v112, v30 offset:956
	s_waitcnt lgkmcnt(0)
	v_cvt_pk_bf16_f32 v8, v8, v113
	v_cvt_pk_bf16_f32 v9, v9, v114
	v_cvt_pk_bf16_f32 v10, v10, v111
	v_cvt_pk_bf16_f32 v11, v11, v112
	v_add_u32_e32 v12, s4, v58
	v_add_u32_e32 v12, 0x5ca00, v12
	v_ashrrev_i32_e32 v13, 31, v12
	v_lshlrev_b64 v[12:13], 10, v[12:13]
	v_lshl_add_u64 v[12:13], s[50:51], 0, v[12:13]
	v_lshl_add_u64 v[12:13], v[12:13], 0, s[6:7]
	v_lshl_add_u64 v[12:13], v[12:13], 0, v[0:1]
	flat_store_dwordx4 v[12:13], v[8:11]
	ds_read_b32 v8, v30 offset:64
	ds_read_b32 v113, v30 offset:196
	ds_read_b32 v9, v30 offset:328
	ds_read_b32 v114, v30 offset:460
	ds_read_b32 v10, v30 offset:592
	ds_read_b32 v111, v30 offset:724
	ds_read_b32 v11, v30 offset:856
	ds_read_b32 v112, v30 offset:988
	s_waitcnt lgkmcnt(0)
	v_cvt_pk_bf16_f32 v8, v8, v113
	v_cvt_pk_bf16_f32 v9, v9, v114
	v_cvt_pk_bf16_f32 v10, v10, v111
	v_cvt_pk_bf16_f32 v11, v11, v112
	v_add_u32_e32 v12, s4, v59
	v_add_u32_e32 v12, 0x5ca00, v12
	v_ashrrev_i32_e32 v13, 31, v12
	v_lshlrev_b64 v[12:13], 10, v[12:13]
	v_lshl_add_u64 v[12:13], s[50:51], 0, v[12:13]
	v_lshl_add_u64 v[12:13], v[12:13], 0, s[6:7]
	v_lshl_add_u64 v[12:13], v[12:13], 0, v[0:1]
	flat_store_dwordx4 v[12:13], v[8:11]
	ds_read_b32 v10, v30 offset:96
	ds_read_b32 v11, v30 offset:228
	ds_read_b32 v14, v30 offset:360
	ds_read_b32 v15, v30 offset:492
	ds_read_b32 v16, v30 offset:624
	ds_read_b32 v17, v30 offset:756
	ds_read_b32 v18, v30 offset:888
	ds_read_b32 v19, v30 offset:1020
	v_add_u32_e32 v8, s4, v60
	v_add_u32_e32 v8, 0x5ca00, v8
	v_ashrrev_i32_e32 v9, 31, v8
	v_lshlrev_b64 v[8:9], 10, v[8:9]
	v_lshl_add_u64 v[12:13], s[50:51], 0, v[8:9]
	v_lshl_add_u64 v[12:13], v[12:13], 0, s[6:7]
	s_waitcnt lgkmcnt(0)
	v_cvt_pk_bf16_f32 v8, v10, v11
	v_cvt_pk_bf16_f32 v9, v14, v15
	v_cvt_pk_bf16_f32 v10, v16, v17
	v_cvt_pk_bf16_f32 v11, v18, v19
	v_lshl_add_u64 v[12:13], v[12:13], 0, v[0:1]
	flat_store_dwordx4 v[12:13], v[8:11]
	s_waitcnt lgkmcnt(0)

; __device__ __forceinline__ void conv_item(const float* W, int K, int N, int kind, int item, const float* gain, unsigned char* Wb, float* scr, int lane) {
;     const int nblk = N / 32, kb = item / nblk, nb = item - kb * nblk, k0 = 64 * kb, n0 = 32 * nb;
;     float wv_[32];
; #pragma unroll
;     for (int i = 0; i < 32; ++i) wv_[i] = W[(size_t)(k0 + 2 * i + (lane >> 5)) * N + n0 + (lane & 31)];
; __global__ void __launch_bounds__(512, 2) mk_fwd(Args a) {
;     ...
;                     if (r < 512) { conv_item(ap->in[16] + L * 1024 * 1024, 1024, 1024, 10, r, nullptr, Wb, scr, lane); continue; } r -= 512;
.LBB0_312:
	s_andn2_b64 vcc, exec, s[4:5]
	s_cbranch_vccnz .LBB0_314
	s_lshl_b32 s4, s79, 5
	s_and_b32 s6, s4, 0xfffffc00
	v_readlane_b32 s4, v254, 40
	v_readlane_b32 s5, v254, 41
	s_load_dwordx2 s[4:5], s[4:5], 0x80
	s_lshl_b32 s7, s73, 1
	v_lshlrev_b32_e32 v0, 2, v4
	s_waitcnt lgkmcnt(0)
	s_add_u32 s12, s4, s52
	s_addc_u32 s13, s5, s53
	s_add_i32 s4, s7, 0xac0
	s_and_b32 s92, s4, 0xffffffc0
	s_sub_i32 s4, s75, s6
	s_add_i32 s4, s4, 0xfffa7600
	s_ashr_i32 s5, s4, 31
	s_lshl_b64 s[6:7], s[4:5], 2
	s_add_u32 s6, s12, s6
	v_or_b32_e32 v10, s92, v3
	s_addc_u32 s7, s13, s7
	v_lshl_add_u64 v[8:9], s[6:7], 0, v[0:1]
	v_lshlrev_b32_e32 v0, 10, v10
	v_lshl_add_u64 v[8:9], v[0:1], 2, v[8:9]
	s_movk_i32 s5, 0x2000
	v_add_co_u32_e32 v10, vcc, s5, v8
	s_movk_i32 s5, 0x4000
	s_nop 0
	v_addc_co_u32_e32 v11, vcc, 0, v9, vcc
	global_load_dword v0, v[8:9], off
	global_load_dword v12, v[10:11], off
	v_add_co_u32_e32 v10, vcc, s5, v8
	s_movk_i32 s5, 0x6000
	s_nop 0
	v_addc_co_u32_e32 v11, vcc, 0, v9, vcc
	global_load_dword v13, v[10:11], off
	v_add_co_u32_e32 v10, vcc, s5, v8
	s_mov_b32 s5, 0x8000
	s_nop 0
	v_addc_co_u32_e32 v11, vcc, 0, v9, vcc
	global_load_dword v14, v[10:11], off
	v_add_co_u32_e32 v10, vcc, s5, v8
	s_mov_b32 s5, 0xa000
	s_nop 0
	v_addc_co_u32_e32 v11, vcc, 0, v9, vcc
	global_load_dword v15, v[10:11], off
	v_add_co_u32_e32 v10, vcc, s5, v8
	s_mov_b32 s5, 0xc000
	s_nop 0
	v_addc_co_u32_e32 v11, vcc, 0, v9, vcc
	global_load_dword v16, v[10:11], off
	v_add_co_u32_e32 v10, vcc, s5, v8
	s_mov_b32 s5, 0xe000
	s_nop 0
	v_addc_co_u32_e32 v11, vcc, 0, v9, vcc
	global_load_dword v17, v[10:11], off
	v_add_co_u32_e32 v10, vcc, s5, v8
	s_mov_b32 s5, 0x10000
	s_nop 0
	v_addc_co_u32_e32 v11, vcc, 0, v9, vcc
	global_load_dword v18, v[10:11], off
	v_add_co_u32_e32 v10, vcc, s5, v8
	s_mov_b32 s5, 0x12000
	s_nop 0
	v_addc_co_u32_e32 v11, vcc, 0, v9, vcc
	global_load_dword v19, v[10:11], off
	v_add_co_u32_e32 v10, vcc, s5, v8
	s_mov_b32 s5, 0x14000
	s_nop 0
	v_addc_co_u32_e32 v11, vcc, 0, v9, vcc
	global_load_dword v20, v[10:11], off
	v_add_co_u32_e32 v10, vcc, s5, v8
	s_mov_b32 s5, 0x16000
	s_nop 0
	v_addc_co_u32_e32 v11, vcc, 0, v9, vcc
	global_load_dword v21, v[10:11], off
	v_add_co_u32_e32 v10, vcc, s5, v8
	s_mov_b32 s5, 0x18000
	s_nop 0
	v_addc_co_u32_e32 v11, vcc, 0, v9, vcc
	global_load_dword v22, v[10:11], off
	v_add_co_u32_e32 v10, vcc, s5, v8
	s_mov_b32 s5, 0x1a000
	s_nop 0
	v_addc_co_u32_e32 v11, vcc, 0, v9, vcc
	global_load_dword v23, v[10:11], off
	v_add_co_u32_e32 v10, vcc, s5, v8
	s_mov_b32 s5, 0x1c000
	s_nop 0
	v_addc_co_u32_e32 v11, vcc, 0, v9, vcc
	global_load_dword v24, v[10:11], off
	v_add_co_u32_e32 v10, vcc, s5, v8
	s_mov_b32 s5, 0x1e000
	s_nop 0
	v_addc_co_u32_e32 v11, vcc, 0, v9, vcc
	global_load_dword v25, v[10:11], off
	v_add_co_u32_e32 v10, vcc, s5, v8
	s_mov_b32 s5, 0x20000
	s_nop 0
	v_addc_co_u32_e32 v11, vcc, 0, v9, vcc
	global_load_dword v26, v[10:11], off
	v_add_co_u32_e32 v10, vcc, s5, v8
	s_mov_b32 s5, 0x22000
	s_nop 0
	v_addc_co_u32_e32 v11, vcc, 0, v9, vcc
	global_load_dword v27, v[10:11], off
	v_add_co_u32_e32 v10, vcc, s5, v8
	s_mov_b32 s5, 0x24000
	s_nop 0
	v_addc_co_u32_e32 v11, vcc, 0, v9, vcc
	global_load_dword v28, v[10:11], off
	v_add_co_u32_e32 v10, vcc, s5, v8
	s_mov_b32 s5, 0x26000
	s_nop 0
	v_addc_co_u32_e32 v11, vcc, 0, v9, vcc
	global_load_dword v29, v[10:11], off
	v_add_co_u32_e32 v10, vcc, s5, v8
	s_mov_b32 s5, 0x28000
	s_nop 0
	v_addc_co_u32_e32 v11, vcc, 0, v9, vcc
	global_load_dword v104, v[10:11], off
	v_add_co_u32_e32 v10, vcc, s5, v8
	s_mov_b32 s5, 0x2a000
	s_nop 0
	v_addc_co_u32_e32 v11, vcc, 0, v9, vcc
	global_load_dword v105, v[10:11], off
	v_add_co_u32_e32 v10, vcc, s5, v8
	s_mov_b32 s5, 0x2c000
	s_nop 0
	v_addc_co_u32_e32 v11, vcc, 0, v9, vcc
	global_load_dword v106, v[10:11], off
	v_add_co_u32_e32 v10, vcc, s5, v8
	s_mov_b32 s5, 0x2e000
	s_nop 0
	v_addc_co_u32_e32 v11, vcc, 0, v9, vcc
	global_load_dword v107, v[10:11], off
	v_add_co_u32_e32 v10, vcc, s5, v8
	s_mov_b32 s5, 0x30000
	s_nop 0
	v_addc_co_u32_e32 v11, vcc, 0, v9, vcc
	global_load_dword v108, v[10:11], off
	v_add_co_u32_e32 v10, vcc, s5, v8
	s_mov_b32 s5, 0x32000
	s_nop 0
	v_addc_co_u32_e32 v11, vcc, 0, v9, vcc
	global_load_dword v109, v[10:11], off
	v_add_co_u32_e32 v10, vcc, s5, v8
	s_mov_b32 s5, 0x34000
	s_nop 0
	v_addc_co_u32_e32 v11, vcc, 0, v9, vcc
	global_load_dword v110, v[10:11], off
	v_add_co_u32_e32 v10, vcc, s5, v8
	s_mov_b32 s5, 0x36000
	s_nop 0
	v_addc_co_u32_e32 v11, vcc, 0, v9, vcc
	global_load_dword v111, v[10:11], off
	v_add_co_u32_e32 v10, vcc, s5, v8
	s_mov_b32 s5, 0x38000
	s_nop 0
	v_addc_co_u32_e32 v11, vcc, 0, v9, vcc
	global_load_dword v112, v[10:11], off
	v_add_co_u32_e32 v10, vcc, s5, v8
	s_mov_b32 s5, 0x3a000
	s_nop 0
	v_addc_co_u32_e32 v11, vcc, 0, v9, vcc
	global_load_dword v113, v[10:11], off
	v_add_co_u32_e32 v10, vcc, s5, v8
	s_mov_b32 s5, 0x3c000
	s_nop 0
	v_addc_co_u32_e32 v11, vcc, 0, v9, vcc
	global_load_dword v114, v[10:11], off
	v_add_co_u32_e32 v10, vcc, s5, v8
	s_mov_b32 s5, 0x3e000
	s_nop 0
	v_addc_co_u32_e32 v11, vcc, 0, v9, vcc
	v_add_co_u32_e32 v8, vcc, s5, v8
	global_load_dword v10, v[10:11], off
	s_nop 0
	v_addc_co_u32_e32 v9, vcc, 0, v9, vcc
	global_load_dword v8, v[8:9], off
	s_waitcnt vmcnt(0)
; __device__ __forceinline__ unsigned pk2(float lo, float hi) { f32x2_t v = {lo, hi}; bf16x2_t b = __builtin_convertvector(v, bf16x2_t); return __builtin_bit_cast(unsigned, b); }
; __device__ __forceinline__ void conv_item(const float* W, int K, int N, int kind, int item, const float* gain, unsigned char* Wb, float* scr, int lane) {
;     ...
; #pragma unroll
;     for (int i = 0; i < 32; ++i) scr[(2 * i + (lane >> 5)) * 33 + (lane & 31)] = wv_[i];
;     __builtin_amdgcn_s_waitcnt(0); asm volatile("" ::: "memory");
;     const int c = lane & 7; float gg[8];
; #pragma unroll
;     for (int e = 0; e < 8; ++e) gg[e] = gain ? gain[k0 + 8 * c + e] : 1.0f;
; #pragma unroll
;     for (int j = 0; j < 4; ++j) { const int n = (lane >> 3) + 8 * j; const float* s = scr + (8 * c) * 33 + n;
;         u32x4 o; o.x = pk2(s[0] * gg[0], s[33] * gg[1]); o.y = pk2(s[2 * 33] * gg[2], s[3 * 33] * gg[3]); o.z = pk2(s[4 * 33] * gg[4], s[5 * 33] * gg[5]); o.w = pk2(s[6 * 33] * gg[6], s[7 * 33] * gg[7]);
;         *(u32x4*)(wdst(kind, n0 + n, Wb) + k0 + 8 * c) = o; }
;     __builtin_amdgcn_s_waitcnt(0); asm volatile("" ::: "memory");
	ds_write2_b32 v5, v0, v12 offset1:66
	ds_write2_b32 v5, v13, v14 offset0:132 offset1:198
	v_add_u32_e32 v0, 0x400, v5
	ds_write2_b32 v0, v15, v16 offset0:8 offset1:74
	ds_write2_b32 v0, v17, v18 offset0:140 offset1:206
	v_add_u32_e32 v0, 0x800, v5
	ds_write2_b32 v0, v19, v20 offset0:16 offset1:82
	ds_write2_b32 v0, v21, v22 offset0:148 offset1:214
	v_add_u32_e32 v0, 0xc00, v5
	ds_write2_b32 v0, v23, v24 offset0:24 offset1:90
	ds_write2_b32 v0, v25, v26 offset0:156 offset1:222
	v_add_u32_e32 v0, 0x1000, v5
	ds_write2_b32 v0, v27, v28 offset0:32 offset1:98
	ds_write2_b32 v0, v29, v104 offset0:164 offset1:230
	v_add_u32_e32 v0, 0x1400, v5
	ds_write2_b32 v0, v105, v106 offset0:40 offset1:106
	ds_write2_b32 v0, v107, v108 offset0:172 offset1:238
	v_add_u32_e32 v0, 0x1800, v5
	ds_write2_b32 v0, v109, v110 offset0:48 offset1:114
	ds_write2_b32 v0, v111, v112 offset0:180 offset1:246
	v_add_u32_e32 v0, 0x1c00, v5
	ds_write2_b32 v0, v113, v114 offset0:56 offset1:122
	ds_write2_b32 v0, v10, v8 offset0:188 offset1:254
	s_waitcnt vmcnt(0) expcnt(0) lgkmcnt(0)
	ds_read_b32 v8, v30
	ds_read_b32 v113, v30 offset:132
	ds_read_b32 v9, v30 offset:264
	ds_read_b32 v114, v30 offset:396
	ds_read_b32 v10, v30 offset:528
	ds_read_b32 v111, v30 offset:660
	ds_read_b32 v11, v30 offset:792
	ds_read_b32 v112, v30 offset:924
	s_lshl_b64 s[6:7], s[92:93], 1
	s_waitcnt lgkmcnt(0)
	v_cvt_pk_bf16_f32 v8, v8, v113
	v_cvt_pk_bf16_f32 v9, v9, v114
	v_cvt_pk_bf16_f32 v10, v10, v111
	v_cvt_pk_bf16_f32 v11, v11, v112
	v_add_u32_e32 v0, s4, v61
	v_add_u32_e32 v12, 0x58a00, v0
	v_ashrrev_i32_e32 v13, 31, v12
	v_lshlrev_b64 v[12:13], 11, v[12:13]
	v_lshl_add_u64 v[12:13], s[54:55], 0, v[12:13]
	v_lshl_add_u64 v[12:13], v[12:13], 0, s[6:7]
	v_lshlrev_b32_e32 v0, 1, v6
	v_lshl_add_u64 v[12:13], v[12:13], 0, v[0:1]
	flat_store_dwordx4 v[12:13], v[8:11]
	ds_read_b32 v8, v30 offset:32
	ds_read_b32 v113, v30 offset:164
	ds_read_b32 v9, v30 offset:296
	ds_read_b32 v114, v30 offset:428
	ds_read_b32 v10, v30 offset:560
	ds_read_b32 v111, v30 offset:692
	ds_read_b32 v11, v30 offset:824
	ds_read_b32 v112, v30 offset:956
	s_waitcnt lgkmcnt(0)
	v_cvt_pk_bf16_f32 v8, v8, v113
	v_cvt_pk_bf16_f32 v9, v9, v114
	v_cvt_pk_bf16_f32 v10, v10, v111
	v_cvt_pk_bf16_f32 v11, v11, v112
	v_add_u32_e32 v12, s4, v62
	v_add_u32_e32 v12, 0x58a00, v12
	v_ashrrev_i32_e32 v13, 31, v12
	v_lshlrev_b64 v[12:13], 11, v[12:13]
	v_lshl_add_u64 v[12:13], s[54:55], 0, v[12:13]
	v_lshl_add_u64 v[12:13], v[12:13], 0, s[6:7]
	v_lshl_add_u64 v[12:13], v[12:13], 0, v[0:1]
	flat_store_dwordx4 v[12:13], v[8:11]
	ds_read_b32 v8, v30 offset:64
	ds_read_b32 v113, v30 offset:196
	ds_read_b32 v9, v30 offset:328
	ds_read_b32 v114, v30 offset:460
	ds_read_b32 v10, v30 offset:592
	ds_read_b32 v111, v30 offset:724
	ds_read_b32 v11, v30 offset:856
	ds_read_b32 v112, v30 offset:988
	s_waitcnt lgkmcnt(0)
	v_cvt_pk_bf16_f32 v8, v8, v113
	v_cvt_pk_bf16_f32 v9, v9, v114
	v_cvt_pk_bf16_f32 v10, v10, v111
	v_cvt_pk_bf16_f32 v11, v11, v112
	v_add_u32_e32 v12, s4, v63
	v_add_u32_e32 v12, 0x58a00, v12
	v_ashrrev_i32_e32 v13, 31, v12
	v_lshlrev_b64 v[12:13], 11, v[12:13]
	v_lshl_add_u64 v[12:13], s[54:55], 0, v[12:13]
	v_lshl_add_u64 v[12:13], v[12:13], 0, s[6:7]
	v_lshl_add_u64 v[12:13], v[12:13], 0, v[0:1]
	flat_store_dwordx4 v[12:13], v[8:11]
	ds_read_b32 v10, v30 offset:96
	ds_read_b32 v11, v30 offset:228
	ds_read_b32 v14, v30 offset:360
	ds_read_b32 v15, v30 offset:492
	ds_read_b32 v16, v30 offset:624
	ds_read_b32 v17, v30 offset:756
	ds_read_b32 v18, v30 offset:888
	ds_read_b32 v19, v30 offset:1020
	v_add_u32_e32 v8, s4, v64
	v_add_u32_e32 v8, 0x58a00, v8
	v_ashrrev_i32_e32 v9, 31, v8
	v_lshlrev_b64 v[8:9], 11, v[8:9]
	v_lshl_add_u64 v[12:13], s[54:55], 0, v[8:9]
	v_lshl_add_u64 v[12:13], v[12:13], 0, s[6:7]
	s_waitcnt lgkmcnt(0)
	v_cvt_pk_bf16_f32 v8, v10, v11
	v_cvt_pk_bf16_f32 v9, v14, v15
	v_cvt_pk_bf16_f32 v10, v16, v17
	v_cvt_pk_bf16_f32 v11, v18, v19
	v_lshl_add_u64 v[12:13], v[12:13], 0, v[0:1]
	flat_store_dwordx4 v[12:13], v[8:11]
	s_waitcnt lgkmcnt(0)

; __device__ __forceinline__ void conv_item(const float* W, int K, int N, int kind, int item, const float* gain, unsigned char* Wb, float* scr, int lane) {
;     const int nblk = N / 32, kb = item / nblk, nb = item - kb * nblk, k0 = 64 * kb, n0 = 32 * nb;
;     float wv_[32];
; #pragma unroll
;     for (int i = 0; i < 32; ++i) wv_[i] = W[(size_t)(k0 + 2 * i + (lane >> 5)) * N + n0 + (lane & 31)];
; __global__ void __launch_bounds__(512, 2) mk_fwd(Args a) {
;     ...
;                     if (r < 1408) { conv_item(ap->in[4] + L * 2816 * 1024, 2816, 1024, 1, r, nullptr, Wb, scr, lane); continue; } r -= 1408;
.LBB0_315:
	s_andn2_b64 vcc, exec, s[4:5]
	s_cbranch_vccnz .LBB0_317
	s_lshl_b32 s4, s80, 5
	s_and_b32 s6, s4, 0xfffffc00
	v_readlane_b32 s4, v254, 40
	v_readlane_b32 s5, v254, 41
	s_load_dwordx2 s[4:5], s[4:5], 0x20
	s_lshl_b32 s7, s73, 1
	v_lshlrev_b32_e32 v0, 2, v4
	s_waitcnt lgkmcnt(0)
	s_add_u32 s12, s4, s3
	s_addc_u32 s13, s5, s67
	s_add_i32 s4, s7, 0x20c0
	s_and_b32 s92, s4, 0xffffffc0
	s_sub_i32 s4, s75, s6
	s_add_i32 s4, s4, 0xfffbd600
	s_ashr_i32 s5, s4, 31
	s_lshl_b64 s[6:7], s[4:5], 2
	s_add_u32 s6, s12, s6
	v_or_b32_e32 v10, s92, v3
	s_addc_u32 s7, s13, s7
	v_lshl_add_u64 v[8:9], s[6:7], 0, v[0:1]
	v_lshlrev_b32_e32 v0, 10, v10
	v_lshl_add_u64 v[8:9], v[0:1], 2, v[8:9]
	s_movk_i32 s5, 0x2000
	v_add_co_u32_e32 v10, vcc, s5, v8
	s_movk_i32 s5, 0x4000
	s_nop 0
	v_addc_co_u32_e32 v11, vcc, 0, v9, vcc
	global_load_dword v0, v[8:9], off
	global_load_dword v12, v[10:11], off
	v_add_co_u32_e32 v10, vcc, s5, v8
	s_movk_i32 s5, 0x6000
	s_nop 0
	v_addc_co_u32_e32 v11, vcc, 0, v9, vcc
	global_load_dword v13, v[10:11], off
	v_add_co_u32_e32 v10, vcc, s5, v8
	s_mov_b32 s5, 0x8000
	s_nop 0
	v_addc_co_u32_e32 v11, vcc, 0, v9, vcc
	global_load_dword v14, v[10:11], off
	v_add_co_u32_e32 v10, vcc, s5, v8
	s_mov_b32 s5, 0xa000
	s_nop 0
	v_addc_co_u32_e32 v11, vcc, 0, v9, vcc
	global_load_dword v15, v[10:11], off
	v_add_co_u32_e32 v10, vcc, s5, v8
	s_mov_b32 s5, 0xc000
	s_nop 0
	v_addc_co_u32_e32 v11, vcc, 0, v9, vcc
	global_load_dword v16, v[10:11], off
	v_add_co_u32_e32 v10, vcc, s5, v8
	s_mov_b32 s5, 0xe000
	s_nop 0
	v_addc_co_u32_e32 v11, vcc, 0, v9, vcc
	global_load_dword v17, v[10:11], off
	v_add_co_u32_e32 v10, vcc, s5, v8
	s_mov_b32 s5, 0x10000
	s_nop 0
	v_addc_co_u32_e32 v11, vcc, 0, v9, vcc
	global_load_dword v18, v[10:11], off
	v_add_co_u32_e32 v10, vcc, s5, v8
	s_mov_b32 s5, 0x12000
	s_nop 0
	v_addc_co_u32_e32 v11, vcc, 0, v9, vcc
	global_load_dword v19, v[10:11], off
	v_add_co_u32_e32 v10, vcc, s5, v8
	s_mov_b32 s5, 0x14000
	s_nop 0
	v_addc_co_u32_e32 v11, vcc, 0, v9, vcc
	global_load_dword v20, v[10:11], off
	v_add_co_u32_e32 v10, vcc, s5, v8
	s_mov_b32 s5, 0x16000
	s_nop 0
	v_addc_co_u32_e32 v11, vcc, 0, v9, vcc
	global_load_dword v21, v[10:11], off
	v_add_co_u32_e32 v10, vcc, s5, v8
	s_mov_b32 s5, 0x18000
	s_nop 0
	v_addc_co_u32_e32 v11, vcc, 0, v9, vcc
	global_load_dword v22, v[10:11], off
	v_add_co_u32_e32 v10, vcc, s5, v8
	s_mov_b32 s5, 0x1a000
	s_nop 0
	v_addc_co_u32_e32 v11, vcc, 0, v9, vcc
	global_load_dword v23, v[10:11], off
	v_add_co_u32_e32 v10, vcc, s5, v8
	s_mov_b32 s5, 0x1c000
	s_nop 0
	v_addc_co_u32_e32 v11, vcc, 0, v9, vcc
	global_load_dword v24, v[10:11], off
	v_add_co_u32_e32 v10, vcc, s5, v8
	s_mov_b32 s5, 0x1e000
	s_nop 0
	v_addc_co_u32_e32 v11, vcc, 0, v9, vcc
	global_load_dword v25, v[10:11], off
	v_add_co_u32_e32 v10, vcc, s5, v8
	s_mov_b32 s5, 0x20000
	s_nop 0
	v_addc_co_u32_e32 v11, vcc, 0, v9, vcc
	global_load_dword v26, v[10:11], off
	v_add_co_u32_e32 v10, vcc, s5, v8
	s_mov_b32 s5, 0x22000
	s_nop 0
	v_addc_co_u32_e32 v11, vcc, 0, v9, vcc
	global_load_dword v27, v[10:11], off
	v_add_co_u32_e32 v10, vcc, s5, v8
	s_mov_b32 s5, 0x24000
	s_nop 0
	v_addc_co_u32_e32 v11, vcc, 0, v9, vcc
	global_load_dword v28, v[10:11], off
	v_add_co_u32_e32 v10, vcc, s5, v8
	s_mov_b32 s5, 0x26000
	s_nop 0
	v_addc_co_u32_e32 v11, vcc, 0, v9, vcc
	global_load_dword v29, v[10:11], off
	v_add_co_u32_e32 v10, vcc, s5, v8
	s_mov_b32 s5, 0x28000
	s_nop 0
	v_addc_co_u32_e32 v11, vcc, 0, v9, vcc
	global_load_dword v104, v[10:11], off
	v_add_co_u32_e32 v10, vcc, s5, v8
	s_mov_b32 s5, 0x2a000
	s_nop 0
	v_addc_co_u32_e32 v11, vcc, 0, v9, vcc
	global_load_dword v105, v[10:11], off
	v_add_co_u32_e32 v10, vcc, s5, v8
	s_mov_b32 s5, 0x2c000
	s_nop 0
	v_addc_co_u32_e32 v11, vcc, 0, v9, vcc
	global_load_dword v106, v[10:11], off
	v_add_co_u32_e32 v10, vcc, s5, v8
	s_mov_b32 s5, 0x2e000
	s_nop 0
	v_addc_co_u32_e32 v11, vcc, 0, v9, vcc
	global_load_dword v107, v[10:11], off
	v_add_co_u32_e32 v10, vcc, s5, v8
	s_mov_b32 s5, 0x30000
	s_nop 0
	v_addc_co_u32_e32 v11, vcc, 0, v9, vcc
	global_load_dword v108, v[10:11], off
	v_add_co_u32_e32 v10, vcc, s5, v8
	s_mov_b32 s5, 0x32000
	s_nop 0
	v_addc_co_u32_e32 v11, vcc, 0, v9, vcc
	global_load_dword v109, v[10:11], off
	v_add_co_u32_e32 v10, vcc, s5, v8
	s_mov_b32 s5, 0x34000
	s_nop 0
	v_addc_co_u32_e32 v11, vcc, 0, v9, vcc
	global_load_dword v110, v[10:11], off
	v_add_co_u32_e32 v10, vcc, s5, v8
	s_mov_b32 s5, 0x36000
	s_nop 0
	v_addc_co_u32_e32 v11, vcc, 0, v9, vcc
	global_load_dword v111, v[10:11], off
	v_add_co_u32_e32 v10, vcc, s5, v8
	s_mov_b32 s5, 0x38000
	s_nop 0
	v_addc_co_u32_e32 v11, vcc, 0, v9, vcc
	global_load_dword v112, v[10:11], off
	v_add_co_u32_e32 v10, vcc, s5, v8
	s_mov_b32 s5, 0x3a000
	s_nop 0
	v_addc_co_u32_e32 v11, vcc, 0, v9, vcc
	global_load_dword v113, v[10:11], off
	v_add_co_u32_e32 v10, vcc, s5, v8
	s_mov_b32 s5, 0x3c000
	s_nop 0
	v_addc_co_u32_e32 v11, vcc, 0, v9, vcc
	global_load_dword v114, v[10:11], off
	v_add_co_u32_e32 v10, vcc, s5, v8
	s_mov_b32 s5, 0x3e000
	s_nop 0
	v_addc_co_u32_e32 v11, vcc, 0, v9, vcc
	v_add_co_u32_e32 v8, vcc, s5, v8
	global_load_dword v10, v[10:11], off
	s_nop 0
	v_addc_co_u32_e32 v9, vcc, 0, v9, vcc
	global_load_dword v8, v[8:9], off
	s_waitcnt vmcnt(0)
; __device__ __forceinline__ unsigned pk2(float lo, float hi) { f32x2_t v = {lo, hi}; bf16x2_t b = __builtin_convertvector(v, bf16x2_t); return __builtin_bit_cast(unsigned, b); }
; __device__ __forceinline__ void conv_item(const float* W, int K, int N, int kind, int item, const float* gain, unsigned char* Wb, float* scr, int lane) {
;     ...
;     for (int i = 0; i < 32; ++i) scr[(2 * i + (lane >> 5)) * 33 + (lane & 31)] = wv_[i];
;     __builtin_amdgcn_s_waitcnt(0); asm volatile("" ::: "memory");
;     const int c = lane & 7; float gg[8];
; #pragma unroll
;     for (int e = 0; e < 8; ++e) gg[e] = gain ? gain[k0 + 8 * c + e] : 1.0f;
; #pragma unroll
;     for (int j = 0; j < 4; ++j) { const int n = (lane >> 3) + 8 * j; const float* s = scr + (8 * c) * 33 + n;
;         u32x4 o; o.x = pk2(s[0] * gg[0], s[33] * gg[1]); o.y = pk2(s[2 * 33] * gg[2], s[3 * 33] * gg[3]); o.z = pk2(s[4 * 33] * gg[4], s[5 * 33] * gg[5]); o.w = pk2(s[6 * 33] * gg[6], s[7 * 33] * gg[7]);
;         *(u32x4*)(wdst(kind, n0 + n, Wb) + k0 + 8 * c) = o; }
	ds_write2_b32 v5, v0, v12 offset1:66
	ds_write2_b32 v5, v13, v14 offset0:132 offset1:198
	v_add_u32_e32 v0, 0x400, v5
	ds_write2_b32 v0, v15, v16 offset0:8 offset1:74
	ds_write2_b32 v0, v17, v18 offset0:140 offset1:206
	v_add_u32_e32 v0, 0x800, v5
	ds_write2_b32 v0, v19, v20 offset0:16 offset1:82
	ds_write2_b32 v0, v21, v22 offset0:148 offset1:214
	v_add_u32_e32 v0, 0xc00, v5
	ds_write2_b32 v0, v23, v24 offset0:24 offset1:90
	ds_write2_b32 v0, v25, v26 offset0:156 offset1:222
	v_add_u32_e32 v0, 0x1000, v5
	ds_write2_b32 v0, v27, v28 offset0:32 offset1:98
	ds_write2_b32 v0, v29, v104 offset0:164 offset1:230
	v_add_u32_e32 v0, 0x1400, v5
	ds_write2_b32 v0, v105, v106 offset0:40 offset1:106
	ds_write2_b32 v0, v107, v108 offset0:172 offset1:238
	v_add_u32_e32 v0, 0x1800, v5
	ds_write2_b32 v0, v109, v110 offset0:48 offset1:114
	ds_write2_b32 v0, v111, v112 offset0:180 offset1:246
	v_add_u32_e32 v0, 0x1c00, v5
	ds_write2_b32 v0, v113, v114 offset0:56 offset1:122
	ds_write2_b32 v0, v10, v8 offset0:188 offset1:254
	s_waitcnt vmcnt(0) expcnt(0) lgkmcnt(0)
	ds_read_b32 v0, v30
	ds_read_b32 v8, v30 offset:132
	v_mov_b64_e32 v[12:13], s[56:57]
	s_movk_i32 s5, 0x1600
	v_add_u32_e32 v18, s4, v68
	v_add_u32_e32 v18, 0x42a00, v18
	s_waitcnt lgkmcnt(0)
	v_cvt_pk_bf16_f32 v8, v0, v8
	ds_read_b32 v0, v30 offset:264
	ds_read_b32 v9, v30 offset:396
	s_waitcnt lgkmcnt(0)
	v_cvt_pk_bf16_f32 v9, v0, v9
	ds_read_b32 v0, v30 offset:528
	ds_read_b32 v10, v30 offset:660
	s_waitcnt lgkmcnt(0)
	v_cvt_pk_bf16_f32 v10, v0, v10
	ds_read_b32 v0, v30 offset:792
	ds_read_b32 v11, v30 offset:924
	s_waitcnt lgkmcnt(0)
	v_cvt_pk_bf16_f32 v11, v0, v11
	v_add_u32_e32 v0, s4, v65
	v_add_u32_e32 v0, 0x42a00, v0
	v_mad_i64_i32 v[14:15], s[6:7], v0, s5, v[12:13]
	s_lshl_b64 s[6:7], s[92:93], 1
	s_nop 0
	v_lshl_add_u64 v[14:15], v[14:15], 0, s[6:7]
	v_lshlrev_b32_e32 v0, 1, v6
	v_lshl_add_u64 v[14:15], v[14:15], 0, v[0:1]
	flat_store_dwordx4 v[14:15], v[8:11]
	ds_read_b32 v8, v30 offset:32
	ds_read_b32 v113, v30 offset:164
	ds_read_b32 v9, v30 offset:296
	ds_read_b32 v114, v30 offset:428
	ds_read_b32 v10, v30 offset:560
	ds_read_b32 v111, v30 offset:692
	ds_read_b32 v11, v30 offset:824
	ds_read_b32 v112, v30 offset:956
	s_waitcnt lgkmcnt(0)
	v_cvt_pk_bf16_f32 v8, v8, v113
	v_cvt_pk_bf16_f32 v9, v9, v114
	v_cvt_pk_bf16_f32 v10, v10, v111
	v_cvt_pk_bf16_f32 v11, v11, v112
	v_add_u32_e32 v14, s4, v66
	v_add_u32_e32 v14, 0x42a00, v14
	v_mad_i64_i32 v[14:15], s[12:13], v14, s5, v[12:13]
	v_lshl_add_u64 v[14:15], v[14:15], 0, s[6:7]
	v_lshl_add_u64 v[14:15], v[14:15], 0, v[0:1]
	flat_store_dwordx4 v[14:15], v[8:11]
	ds_read_b32 v8, v30 offset:64
	ds_read_b32 v113, v30 offset:196
	ds_read_b32 v9, v30 offset:328
	ds_read_b32 v114, v30 offset:460
	ds_read_b32 v10, v30 offset:592
	ds_read_b32 v111, v30 offset:724
	ds_read_b32 v11, v30 offset:856
	ds_read_b32 v112, v30 offset:988
	s_waitcnt lgkmcnt(0)
	v_cvt_pk_bf16_f32 v8, v8, v113
	v_cvt_pk_bf16_f32 v9, v9, v114
	v_cvt_pk_bf16_f32 v10, v10, v111
	v_cvt_pk_bf16_f32 v11, v11, v112
	v_add_u32_e32 v14, s4, v67
	v_add_u32_e32 v14, 0x42a00, v14
	v_mad_i64_i32 v[14:15], s[12:13], v14, s5, v[12:13]
	v_lshl_add_u64 v[14:15], v[14:15], 0, s[6:7]
	v_lshl_add_u64 v[14:15], v[14:15], 0, v[0:1]
	flat_store_dwordx4 v[14:15], v[8:11]
	ds_read_b32 v8, v30 offset:96
	ds_read_b32 v9, v30 offset:228
	ds_read_b32 v10, v30 offset:360
	ds_read_b32 v11, v30 offset:492
	ds_read_b32 v14, v30 offset:624
	ds_read_b32 v15, v30 offset:756
	ds_read_b32 v16, v30 offset:888
	ds_read_b32 v17, v30 offset:1020
	v_mad_i64_i32 v[12:13], s[4:5], v18, s5, v[12:13]
	v_lshl_add_u64 v[12:13], v[12:13], 0, s[6:7]
	s_waitcnt lgkmcnt(0)
	v_cvt_pk_bf16_f32 v8, v8, v9
	v_cvt_pk_bf16_f32 v9, v10, v11
	v_cvt_pk_bf16_f32 v10, v14, v15
	v_cvt_pk_bf16_f32 v11, v16, v17
	v_lshl_add_u64 v[12:13], v[12:13], 0, v[0:1]
	flat_store_dwordx4 v[12:13], v[8:11]
	s_waitcnt lgkmcnt(0)

; __device__ __forceinline__ void conv_item(const float* W, int K, int N, int kind, int item, const float* gain, unsigned char* Wb, float* scr, int lane) {
;     const int nblk = N / 32, kb = item / nblk, nb = item - kb * nblk, k0 = 64 * kb, n0 = 32 * nb;
;     float wv_[32];
; #pragma unroll
;     for (int i = 0; i < 32; ++i) wv_[i] = W[(size_t)(k0 + 2 * i + (lane >> 5)) * N + n0 + (lane & 31)];
; __global__ void __launch_bounds__(512, 2) mk_fwd(Args a) {
;     ...
;                     if (r < 256) { conv_item(ap->in[15] + L * 512 * 1024, 512, 1024, 9, r, nullptr, Wb, scr, lane); continue; } r -= 256;
.LBB0_1207:
	s_andn2_b64 vcc, exec, s[4:5]
	s_cbranch_vccnz .LBB0_1209
	s_lshl_b32 s4, s76, 5
	s_and_b32 s6, s4, 0xfffffc00
	v_readlane_b32 s4, v254, 40
	v_readlane_b32 s5, v254, 41
	s_load_dwordx2 s[4:5], s[4:5], 0x78
	s_lshl_b32 s7, s73, 1
	v_lshlrev_b32_e32 v0, 2, v2
	s_waitcnt lgkmcnt(0)
	s_add_u32 s12, s4, s46
	s_addc_u32 s13, s5, s47
	s_add_i32 s4, s7, 0x2c0
	s_and_b32 s92, s4, 0xffffffc0
	s_sub_i32 s4, s75, s6
	s_add_i32 s4, s4, 0xfff9f600
	s_ashr_i32 s5, s4, 31
	s_lshl_b64 s[6:7], s[4:5], 2
	s_add_u32 s6, s12, s6
	v_or_b32_e32 v8, s92, v3
	s_addc_u32 s7, s13, s7
	v_lshl_add_u64 v[6:7], s[6:7], 0, v[0:1]
	v_lshlrev_b32_e32 v0, 10, v8
	v_lshl_add_u64 v[6:7], v[0:1], 2, v[6:7]
	s_movk_i32 s5, 0x2000
	v_add_co_u32_e32 v8, vcc, s5, v6
	s_movk_i32 s5, 0x4000
	s_nop 0
	v_addc_co_u32_e32 v9, vcc, 0, v7, vcc
	global_load_dword v0, v[6:7], off
	global_load_dword v10, v[8:9], off
	v_add_co_u32_e32 v8, vcc, s5, v6
	s_movk_i32 s5, 0x6000
	s_nop 0
	v_addc_co_u32_e32 v9, vcc, 0, v7, vcc
	global_load_dword v11, v[8:9], off
	v_add_co_u32_e32 v8, vcc, s5, v6
	s_mov_b32 s5, 0x8000
	s_nop 0
	v_addc_co_u32_e32 v9, vcc, 0, v7, vcc
	global_load_dword v12, v[8:9], off
	v_add_co_u32_e32 v8, vcc, s5, v6
	s_mov_b32 s5, 0xa000
	s_nop 0
	v_addc_co_u32_e32 v9, vcc, 0, v7, vcc
	global_load_dword v13, v[8:9], off
	v_add_co_u32_e32 v8, vcc, s5, v6
	s_mov_b32 s5, 0xc000
	s_nop 0
	v_addc_co_u32_e32 v9, vcc, 0, v7, vcc
	global_load_dword v14, v[8:9], off
	v_add_co_u32_e32 v8, vcc, s5, v6
	s_mov_b32 s5, 0xe000
	s_nop 0
	v_addc_co_u32_e32 v9, vcc, 0, v7, vcc
	global_load_dword v15, v[8:9], off
	v_add_co_u32_e32 v8, vcc, s5, v6
	s_mov_b32 s5, 0x10000
	s_nop 0
	v_addc_co_u32_e32 v9, vcc, 0, v7, vcc
	global_load_dword v16, v[8:9], off
	v_add_co_u32_e32 v8, vcc, s5, v6
	s_mov_b32 s5, 0x12000
	s_nop 0
	v_addc_co_u32_e32 v9, vcc, 0, v7, vcc
	global_load_dword v17, v[8:9], off
	v_add_co_u32_e32 v8, vcc, s5, v6
	s_mov_b32 s5, 0x14000
	s_nop 0
	v_addc_co_u32_e32 v9, vcc, 0, v7, vcc
	global_load_dword v18, v[8:9], off
	v_add_co_u32_e32 v8, vcc, s5, v6
	s_mov_b32 s5, 0x16000
	s_nop 0
	v_addc_co_u32_e32 v9, vcc, 0, v7, vcc
	global_load_dword v19, v[8:9], off
	v_add_co_u32_e32 v8, vcc, s5, v6
	s_mov_b32 s5, 0x18000
	s_nop 0
	v_addc_co_u32_e32 v9, vcc, 0, v7, vcc
	global_load_dword v20, v[8:9], off
	v_add_co_u32_e32 v8, vcc, s5, v6
	s_mov_b32 s5, 0x1a000
	s_nop 0
	v_addc_co_u32_e32 v9, vcc, 0, v7, vcc
	global_load_dword v21, v[8:9], off
	v_add_co_u32_e32 v8, vcc, s5, v6
	s_mov_b32 s5, 0x1c000
	s_nop 0
	v_addc_co_u32_e32 v9, vcc, 0, v7, vcc
	global_load_dword v22, v[8:9], off
	v_add_co_u32_e32 v8, vcc, s5, v6
	s_mov_b32 s5, 0x1e000
	s_nop 0
	v_addc_co_u32_e32 v9, vcc, 0, v7, vcc
	global_load_dword v23, v[8:9], off
	v_add_co_u32_e32 v8, vcc, s5, v6
	s_mov_b32 s5, 0x20000
	s_nop 0
	v_addc_co_u32_e32 v9, vcc, 0, v7, vcc
	global_load_dword v24, v[8:9], off
	v_add_co_u32_e32 v8, vcc, s5, v6
	s_mov_b32 s5, 0x22000
	s_nop 0
	v_addc_co_u32_e32 v9, vcc, 0, v7, vcc
	global_load_dword v25, v[8:9], off
	v_add_co_u32_e32 v8, vcc, s5, v6
	s_mov_b32 s5, 0x24000
	s_nop 0
	v_addc_co_u32_e32 v9, vcc, 0, v7, vcc
	global_load_dword v26, v[8:9], off
	v_add_co_u32_e32 v8, vcc, s5, v6
	s_mov_b32 s5, 0x26000
	s_nop 0
	v_addc_co_u32_e32 v9, vcc, 0, v7, vcc
	global_load_dword v27, v[8:9], off
	v_add_co_u32_e32 v8, vcc, s5, v6
	s_mov_b32 s5, 0x28000
	s_nop 0
	v_addc_co_u32_e32 v9, vcc, 0, v7, vcc
	global_load_dword v103, v[8:9], off
	v_add_co_u32_e32 v8, vcc, s5, v6
	s_mov_b32 s5, 0x2a000
	s_nop 0
	v_addc_co_u32_e32 v9, vcc, 0, v7, vcc
	global_load_dword v104, v[8:9], off
	v_add_co_u32_e32 v8, vcc, s5, v6
	s_mov_b32 s5, 0x2c000
	s_nop 0
	v_addc_co_u32_e32 v9, vcc, 0, v7, vcc
	global_load_dword v105, v[8:9], off
	v_add_co_u32_e32 v8, vcc, s5, v6
	s_mov_b32 s5, 0x2e000
	s_nop 0
	v_addc_co_u32_e32 v9, vcc, 0, v7, vcc
	global_load_dword v106, v[8:9], off
	v_add_co_u32_e32 v8, vcc, s5, v6
	s_mov_b32 s5, 0x30000
	s_nop 0
	v_addc_co_u32_e32 v9, vcc, 0, v7, vcc
	global_load_dword v107, v[8:9], off
	v_add_co_u32_e32 v8, vcc, s5, v6
	s_mov_b32 s5, 0x32000
	s_nop 0
	v_addc_co_u32_e32 v9, vcc, 0, v7, vcc
	global_load_dword v108, v[8:9], off
	v_add_co_u32_e32 v8, vcc, s5, v6
	s_mov_b32 s5, 0x34000
	s_nop 0
	v_addc_co_u32_e32 v9, vcc, 0, v7, vcc
	global_load_dword v109, v[8:9], off
	v_add_co_u32_e32 v8, vcc, s5, v6
	s_mov_b32 s5, 0x36000
	s_nop 0
	v_addc_co_u32_e32 v9, vcc, 0, v7, vcc
	global_load_dword v110, v[8:9], off
	v_add_co_u32_e32 v8, vcc, s5, v6
	s_mov_b32 s5, 0x38000
	s_nop 0
	v_addc_co_u32_e32 v9, vcc, 0, v7, vcc
	global_load_dword v111, v[8:9], off
	v_add_co_u32_e32 v8, vcc, s5, v6
	s_mov_b32 s5, 0x3a000
	s_nop 0
	v_addc_co_u32_e32 v9, vcc, 0, v7, vcc
	global_load_dword v112, v[8:9], off
	v_add_co_u32_e32 v8, vcc, s5, v6
	s_mov_b32 s5, 0x3c000
	s_nop 0
	v_addc_co_u32_e32 v9, vcc, 0, v7, vcc
	global_load_dword v113, v[8:9], off
	v_add_co_u32_e32 v8, vcc, s5, v6
	s_mov_b32 s5, 0x3e000
	s_nop 0
	v_addc_co_u32_e32 v9, vcc, 0, v7, vcc
	v_add_co_u32_e32 v6, vcc, s5, v6
	global_load_dword v8, v[8:9], off
	s_nop 0
	v_addc_co_u32_e32 v7, vcc, 0, v7, vcc
	global_load_dword v6, v[6:7], off
	s_waitcnt vmcnt(0)
; __device__ __forceinline__ unsigned pk2(float lo, float hi) { f32x2_t v = {lo, hi}; bf16x2_t b = __builtin_convertvector(v, bf16x2_t); return __builtin_bit_cast(unsigned, b); }
; __device__ __forceinline__ void conv_item(const float* W, int K, int N, int kind, int item, const float* gain, unsigned char* Wb, float* scr, int lane) {
;     ...
;     for (int i = 0; i < 32; ++i) scr[(2 * i + (lane >> 5)) * 33 + (lane & 31)] = wv_[i];
;     __builtin_amdgcn_s_waitcnt(0); asm volatile("" ::: "memory");
;     const int c = lane & 7; float gg[8];
; #pragma unroll
;     for (int e = 0; e < 8; ++e) gg[e] = gain ? gain[k0 + 8 * c + e] : 1.0f;
; #pragma unroll
;     for (int j = 0; j < 4; ++j) { const int n = (lane >> 3) + 8 * j; const float* s = scr + (8 * c) * 33 + n;
;         u32x4 o; o.x = pk2(s[0] * gg[0], s[33] * gg[1]); o.y = pk2(s[2 * 33] * gg[2], s[3 * 33] * gg[3]); o.z = pk2(s[4 * 33] * gg[4], s[5 * 33] * gg[5]); o.w = pk2(s[6 * 33] * gg[6], s[7 * 33] * gg[7]);
;         *(u32x4*)(wdst(kind, n0 + n, Wb) + k0 + 8 * c) = o; }
	ds_write2_b32 v5, v0, v10 offset1:66
	ds_write2_b32 v5, v11, v12 offset0:132 offset1:198
	v_add_u32_e32 v0, 0x400, v5
	ds_write2_b32 v0, v13, v14 offset0:8 offset1:74
	ds_write2_b32 v0, v15, v16 offset0:140 offset1:206
	v_add_u32_e32 v0, 0x800, v5
	ds_write2_b32 v0, v17, v18 offset0:16 offset1:82
	ds_write2_b32 v0, v19, v20 offset0:148 offset1:214
	v_add_u32_e32 v0, 0xc00, v5
	ds_write2_b32 v0, v21, v22 offset0:24 offset1:90
	ds_write2_b32 v0, v23, v24 offset0:156 offset1:222
	v_add_u32_e32 v0, 0x1000, v5
	ds_write2_b32 v0, v25, v26 offset0:32 offset1:98
	ds_write2_b32 v0, v27, v103 offset0:164 offset1:230
	v_add_u32_e32 v0, 0x1400, v5
	ds_write2_b32 v0, v104, v105 offset0:40 offset1:106
	ds_write2_b32 v0, v106, v107 offset0:172 offset1:238
	v_add_u32_e32 v0, 0x1800, v5
	ds_write2_b32 v0, v108, v109 offset0:48 offset1:114
	ds_write2_b32 v0, v110, v111 offset0:180 offset1:246
	v_add_u32_e32 v0, 0x1c00, v5
	ds_write2_b32 v0, v112, v113 offset0:56 offset1:122
	ds_write2_b32 v0, v8, v6 offset0:188 offset1:254
	s_waitcnt vmcnt(0) expcnt(0) lgkmcnt(0)
	ds_read_b32 v6, v29
	ds_read_b32 v112, v29 offset:132
	ds_read_b32 v7, v29 offset:264
	ds_read_b32 v113, v29 offset:396
	ds_read_b32 v8, v29 offset:528
	ds_read_b32 v110, v29 offset:660
	ds_read_b32 v9, v29 offset:792
	ds_read_b32 v111, v29 offset:924
	s_lshl_b64 s[6:7], s[92:93], 1
	s_waitcnt lgkmcnt(0)
	v_cvt_pk_bf16_f32 v6, v6, v112
	v_cvt_pk_bf16_f32 v7, v7, v113
	v_cvt_pk_bf16_f32 v8, v8, v110
	v_cvt_pk_bf16_f32 v9, v9, v111
	v_add_u32_e32 v0, s4, v48
	v_add_u32_e32 v10, 0x60a00, v0
	v_ashrrev_i32_e32 v11, 31, v10
	v_lshlrev_b64 v[10:11], 10, v[10:11]
	v_lshl_add_u64 v[10:11], s[48:49], 0, v[10:11]
	v_lshl_add_u64 v[10:11], v[10:11], 0, s[6:7]
	v_lshlrev_b32_e32 v0, 1, v4
	v_lshl_add_u64 v[10:11], v[10:11], 0, v[0:1]
	flat_store_dwordx4 v[10:11], v[6:9]
	ds_read_b32 v6, v29 offset:32
	ds_read_b32 v112, v29 offset:164
	ds_read_b32 v7, v29 offset:296
	ds_read_b32 v113, v29 offset:428
	ds_read_b32 v8, v29 offset:560
	ds_read_b32 v110, v29 offset:692
	ds_read_b32 v9, v29 offset:824
	ds_read_b32 v111, v29 offset:956
	s_waitcnt lgkmcnt(0)
	v_cvt_pk_bf16_f32 v6, v6, v112
	v_cvt_pk_bf16_f32 v7, v7, v113
	v_cvt_pk_bf16_f32 v8, v8, v110
	v_cvt_pk_bf16_f32 v9, v9, v111
	v_add_u32_e32 v10, s4, v49
	v_add_u32_e32 v10, 0x60a00, v10
	v_ashrrev_i32_e32 v11, 31, v10
	v_lshlrev_b64 v[10:11], 10, v[10:11]
	v_lshl_add_u64 v[10:11], s[48:49], 0, v[10:11]
	v_lshl_add_u64 v[10:11], v[10:11], 0, s[6:7]
	v_lshl_add_u64 v[10:11], v[10:11], 0, v[0:1]
	flat_store_dwordx4 v[10:11], v[6:9]
	ds_read_b32 v6, v29 offset:64
	ds_read_b32 v112, v29 offset:196
	ds_read_b32 v7, v29 offset:328
	ds_read_b32 v113, v29 offset:460
	ds_read_b32 v8, v29 offset:592
	ds_read_b32 v110, v29 offset:724
	ds_read_b32 v9, v29 offset:856
	ds_read_b32 v111, v29 offset:988
	s_waitcnt lgkmcnt(0)
	v_cvt_pk_bf16_f32 v6, v6, v112
	v_cvt_pk_bf16_f32 v7, v7, v113
	v_cvt_pk_bf16_f32 v8, v8, v110
	v_cvt_pk_bf16_f32 v9, v9, v111
	v_add_u32_e32 v10, s4, v50
	v_add_u32_e32 v10, 0x60a00, v10
	v_ashrrev_i32_e32 v11, 31, v10
	v_lshlrev_b64 v[10:11], 10, v[10:11]
	v_lshl_add_u64 v[10:11], s[48:49], 0, v[10:11]
	v_lshl_add_u64 v[10:11], v[10:11], 0, s[6:7]
	v_lshl_add_u64 v[10:11], v[10:11], 0, v[0:1]
	flat_store_dwordx4 v[10:11], v[6:9]
	ds_read_b32 v8, v29 offset:96
	ds_read_b32 v9, v29 offset:228
	ds_read_b32 v12, v29 offset:360
	ds_read_b32 v13, v29 offset:492
	ds_read_b32 v14, v29 offset:624
	ds_read_b32 v15, v29 offset:756
	ds_read_b32 v16, v29 offset:888
	ds_read_b32 v17, v29 offset:1020
	v_add_u32_e32 v6, s4, v51
	v_add_u32_e32 v6, 0x60a00, v6
	v_ashrrev_i32_e32 v7, 31, v6
	v_lshlrev_b64 v[6:7], 10, v[6:7]
	v_lshl_add_u64 v[10:11], s[48:49], 0, v[6:7]
	v_lshl_add_u64 v[10:11], v[10:11], 0, s[6:7]
	s_waitcnt lgkmcnt(0)
	v_cvt_pk_bf16_f32 v6, v8, v9
	v_cvt_pk_bf16_f32 v7, v12, v13
	v_cvt_pk_bf16_f32 v8, v14, v15
	v_cvt_pk_bf16_f32 v9, v16, v17
	v_lshl_add_u64 v[10:11], v[10:11], 0, v[0:1]
	flat_store_dwordx4 v[10:11], v[6:9]
	s_waitcnt lgkmcnt(0)

; __device__ __forceinline__ void conv_item(const float* W, int K, int N, int kind, int item, const float* gain, unsigned char* Wb, float* scr, int lane) {
;     const int nblk = N / 32, kb = item / nblk, nb = item - kb * nblk, k0 = 64 * kb, n0 = 32 * nb;
;     float wv_[32];
; #pragma unroll
;     for (int i = 0; i < 32; ++i) wv_[i] = W[(size_t)(k0 + 2 * i + (lane >> 5)) * N + n0 + (lane & 31)];
; __global__ void __launch_bounds__(512, 2) mk_fwd(Args a) {
;     ...
;                     if (r < 256) { conv_item(ap->in[13] + L * 512 * 1024, 512, 1024, 8, r, nullptr, Wb, scr, lane); continue; } r -= 256;
.LBB0_1210:
	s_andn2_b64 vcc, exec, s[4:5]
	s_cbranch_vccnz .LBB0_1212
	s_lshl_b32 s4, s77, 5
	s_and_b32 s6, s4, 0xfffffc00
	v_readlane_b32 s4, v254, 40
	v_readlane_b32 s5, v254, 41
	s_load_dwordx2 s[4:5], s[4:5], 0x68
	s_lshl_b32 s7, s73, 1
	v_lshlrev_b32_e32 v0, 2, v2
	s_waitcnt lgkmcnt(0)
	s_add_u32 s12, s4, s46
	s_addc_u32 s13, s5, s47
	s_add_i32 s4, s7, 0x4c0
	s_and_b32 s92, s4, 0xffffffc0
	s_sub_i32 s4, s75, s6
	s_add_i32 s4, s4, 0xfffa1600
	s_ashr_i32 s5, s4, 31
	s_lshl_b64 s[6:7], s[4:5], 2
	s_add_u32 s6, s12, s6
	v_or_b32_e32 v8, s92, v3
	s_addc_u32 s7, s13, s7
	v_lshl_add_u64 v[6:7], s[6:7], 0, v[0:1]
	v_lshlrev_b32_e32 v0, 10, v8
	v_lshl_add_u64 v[6:7], v[0:1], 2, v[6:7]
	s_movk_i32 s5, 0x2000
	v_add_co_u32_e32 v8, vcc, s5, v6
	s_movk_i32 s5, 0x4000
	s_nop 0
	v_addc_co_u32_e32 v9, vcc, 0, v7, vcc
	global_load_dword v0, v[6:7], off
	global_load_dword v10, v[8:9], off
	v_add_co_u32_e32 v8, vcc, s5, v6
	s_movk_i32 s5, 0x6000
	s_nop 0
	v_addc_co_u32_e32 v9, vcc, 0, v7, vcc
	global_load_dword v11, v[8:9], off
	v_add_co_u32_e32 v8, vcc, s5, v6
	s_mov_b32 s5, 0x8000
	s_nop 0
	v_addc_co_u32_e32 v9, vcc, 0, v7, vcc
	global_load_dword v12, v[8:9], off
	v_add_co_u32_e32 v8, vcc, s5, v6
	s_mov_b32 s5, 0xa000
	s_nop 0
	v_addc_co_u32_e32 v9, vcc, 0, v7, vcc
	global_load_dword v13, v[8:9], off
	v_add_co_u32_e32 v8, vcc, s5, v6
	s_mov_b32 s5, 0xc000
	s_nop 0
	v_addc_co_u32_e32 v9, vcc, 0, v7, vcc
	global_load_dword v14, v[8:9], off
	v_add_co_u32_e32 v8, vcc, s5, v6
	s_mov_b32 s5, 0xe000
	s_nop 0
	v_addc_co_u32_e32 v9, vcc, 0, v7, vcc
	global_load_dword v15, v[8:9], off
	v_add_co_u32_e32 v8, vcc, s5, v6
	s_mov_b32 s5, 0x10000
	s_nop 0
	v_addc_co_u32_e32 v9, vcc, 0, v7, vcc
	global_load_dword v16, v[8:9], off
	v_add_co_u32_e32 v8, vcc, s5, v6
	s_mov_b32 s5, 0x12000
	s_nop 0
	v_addc_co_u32_e32 v9, vcc, 0, v7, vcc
	global_load_dword v17, v[8:9], off
	v_add_co_u32_e32 v8, vcc, s5, v6
	s_mov_b32 s5, 0x14000
	s_nop 0
	v_addc_co_u32_e32 v9, vcc, 0, v7, vcc
	global_load_dword v18, v[8:9], off
	v_add_co_u32_e32 v8, vcc, s5, v6
	s_mov_b32 s5, 0x16000
	s_nop 0
	v_addc_co_u32_e32 v9, vcc, 0, v7, vcc
	global_load_dword v19, v[8:9], off
	v_add_co_u32_e32 v8, vcc, s5, v6
	s_mov_b32 s5, 0x18000
	s_nop 0
	v_addc_co_u32_e32 v9, vcc, 0, v7, vcc
	global_load_dword v20, v[8:9], off
	v_add_co_u32_e32 v8, vcc, s5, v6
	s_mov_b32 s5, 0x1a000
	s_nop 0
	v_addc_co_u32_e32 v9, vcc, 0, v7, vcc
	global_load_dword v21, v[8:9], off
	v_add_co_u32_e32 v8, vcc, s5, v6
	s_mov_b32 s5, 0x1c000
	s_nop 0
	v_addc_co_u32_e32 v9, vcc, 0, v7, vcc
	global_load_dword v22, v[8:9], off
	v_add_co_u32_e32 v8, vcc, s5, v6
	s_mov_b32 s5, 0x1e000
	s_nop 0
	v_addc_co_u32_e32 v9, vcc, 0, v7, vcc
	global_load_dword v23, v[8:9], off
	v_add_co_u32_e32 v8, vcc, s5, v6
	s_mov_b32 s5, 0x20000
	s_nop 0
	v_addc_co_u32_e32 v9, vcc, 0, v7, vcc
	global_load_dword v24, v[8:9], off
	v_add_co_u32_e32 v8, vcc, s5, v6
	s_mov_b32 s5, 0x22000
	s_nop 0
	v_addc_co_u32_e32 v9, vcc, 0, v7, vcc
	global_load_dword v25, v[8:9], off
	v_add_co_u32_e32 v8, vcc, s5, v6
	s_mov_b32 s5, 0x24000
	s_nop 0
	v_addc_co_u32_e32 v9, vcc, 0, v7, vcc
	global_load_dword v26, v[8:9], off
	v_add_co_u32_e32 v8, vcc, s5, v6
	s_mov_b32 s5, 0x26000
	s_nop 0
	v_addc_co_u32_e32 v9, vcc, 0, v7, vcc
	global_load_dword v27, v[8:9], off
	v_add_co_u32_e32 v8, vcc, s5, v6
	s_mov_b32 s5, 0x28000
	s_nop 0
	v_addc_co_u32_e32 v9, vcc, 0, v7, vcc
	global_load_dword v103, v[8:9], off
	v_add_co_u32_e32 v8, vcc, s5, v6
	s_mov_b32 s5, 0x2a000
	s_nop 0
	v_addc_co_u32_e32 v9, vcc, 0, v7, vcc
	global_load_dword v104, v[8:9], off
	v_add_co_u32_e32 v8, vcc, s5, v6
	s_mov_b32 s5, 0x2c000
	s_nop 0
	v_addc_co_u32_e32 v9, vcc, 0, v7, vcc
	global_load_dword v105, v[8:9], off
	v_add_co_u32_e32 v8, vcc, s5, v6
	s_mov_b32 s5, 0x2e000
	s_nop 0
	v_addc_co_u32_e32 v9, vcc, 0, v7, vcc
	global_load_dword v106, v[8:9], off
	v_add_co_u32_e32 v8, vcc, s5, v6
	s_mov_b32 s5, 0x30000
	s_nop 0
	v_addc_co_u32_e32 v9, vcc, 0, v7, vcc
	global_load_dword v107, v[8:9], off
	v_add_co_u32_e32 v8, vcc, s5, v6
	s_mov_b32 s5, 0x32000
	s_nop 0
	v_addc_co_u32_e32 v9, vcc, 0, v7, vcc
	global_load_dword v108, v[8:9], off
	v_add_co_u32_e32 v8, vcc, s5, v6
	s_mov_b32 s5, 0x34000
	s_nop 0
	v_addc_co_u32_e32 v9, vcc, 0, v7, vcc
	global_load_dword v109, v[8:9], off
	v_add_co_u32_e32 v8, vcc, s5, v6
	s_mov_b32 s5, 0x36000
	s_nop 0
	v_addc_co_u32_e32 v9, vcc, 0, v7, vcc
	global_load_dword v110, v[8:9], off
	v_add_co_u32_e32 v8, vcc, s5, v6
	s_mov_b32 s5, 0x38000
	s_nop 0
	v_addc_co_u32_e32 v9, vcc, 0, v7, vcc
	global_load_dword v111, v[8:9], off
	v_add_co_u32_e32 v8, vcc, s5, v6
	s_mov_b32 s5, 0x3a000
	s_nop 0
	v_addc_co_u32_e32 v9, vcc, 0, v7, vcc
	global_load_dword v112, v[8:9], off
	v_add_co_u32_e32 v8, vcc, s5, v6
	s_mov_b32 s5, 0x3c000
	s_nop 0
	v_addc_co_u32_e32 v9, vcc, 0, v7, vcc
	global_load_dword v113, v[8:9], off
	v_add_co_u32_e32 v8, vcc, s5, v6
	s_mov_b32 s5, 0x3e000
	s_nop 0
	v_addc_co_u32_e32 v9, vcc, 0, v7, vcc
	v_add_co_u32_e32 v6, vcc, s5, v6
	global_load_dword v8, v[8:9], off
	s_nop 0
	v_addc_co_u32_e32 v7, vcc, 0, v7, vcc
	global_load_dword v6, v[6:7], off
	s_waitcnt vmcnt(0)
; __device__ __forceinline__ unsigned pk2(float lo, float hi) { f32x2_t v = {lo, hi}; bf16x2_t b = __builtin_convertvector(v, bf16x2_t); return __builtin_bit_cast(unsigned, b); }
; __device__ __forceinline__ void conv_item(const float* W, int K, int N, int kind, int item, const float* gain, unsigned char* Wb, float* scr, int lane) {
;     ...
;     for (int i = 0; i < 32; ++i) scr[(2 * i + (lane >> 5)) * 33 + (lane & 31)] = wv_[i];
;     __builtin_amdgcn_s_waitcnt(0); asm volatile("" ::: "memory");
;     const int c = lane & 7; float gg[8];
; #pragma unroll
;     for (int e = 0; e < 8; ++e) gg[e] = gain ? gain[k0 + 8 * c + e] : 1.0f;
; #pragma unroll
;     for (int j = 0; j < 4; ++j) { const int n = (lane >> 3) + 8 * j; const float* s = scr + (8 * c) * 33 + n;
;         u32x4 o; o.x = pk2(s[0] * gg[0], s[33] * gg[1]); o.y = pk2(s[2 * 33] * gg[2], s[3 * 33] * gg[3]); o.z = pk2(s[4 * 33] * gg[4], s[5 * 33] * gg[5]); o.w = pk2(s[6 * 33] * gg[6], s[7 * 33] * gg[7]);
;         *(u32x4*)(wdst(kind, n0 + n, Wb) + k0 + 8 * c) = o; }
	ds_write2_b32 v5, v0, v10 offset1:66
	ds_write2_b32 v5, v11, v12 offset0:132 offset1:198
	v_add_u32_e32 v0, 0x400, v5
	ds_write2_b32 v0, v13, v14 offset0:8 offset1:74
	ds_write2_b32 v0, v15, v16 offset0:140 offset1:206
	v_add_u32_e32 v0, 0x800, v5
	ds_write2_b32 v0, v17, v18 offset0:16 offset1:82
	ds_write2_b32 v0, v19, v20 offset0:148 offset1:214
	v_add_u32_e32 v0, 0xc00, v5
	ds_write2_b32 v0, v21, v22 offset0:24 offset1:90
	ds_write2_b32 v0, v23, v24 offset0:156 offset1:222
	v_add_u32_e32 v0, 0x1000, v5
	ds_write2_b32 v0, v25, v26 offset0:32 offset1:98
	ds_write2_b32 v0, v27, v103 offset0:164 offset1:230
	v_add_u32_e32 v0, 0x1400, v5
	ds_write2_b32 v0, v104, v105 offset0:40 offset1:106
	ds_write2_b32 v0, v106, v107 offset0:172 offset1:238
	v_add_u32_e32 v0, 0x1800, v5
	ds_write2_b32 v0, v108, v109 offset0:48 offset1:114
	ds_write2_b32 v0, v110, v111 offset0:180 offset1:246
	v_add_u32_e32 v0, 0x1c00, v5
	ds_write2_b32 v0, v112, v113 offset0:56 offset1:122
	ds_write2_b32 v0, v8, v6 offset0:188 offset1:254
	s_waitcnt vmcnt(0) expcnt(0) lgkmcnt(0)
	ds_read_b32 v6, v29
	ds_read_b32 v112, v29 offset:132
	ds_read_b32 v7, v29 offset:264
	ds_read_b32 v113, v29 offset:396
	ds_read_b32 v8, v29 offset:528
	ds_read_b32 v110, v29 offset:660
	ds_read_b32 v9, v29 offset:792
	ds_read_b32 v111, v29 offset:924
	s_lshl_b64 s[6:7], s[92:93], 1
	s_waitcnt lgkmcnt(0)
	v_cvt_pk_bf16_f32 v6, v6, v112
	v_cvt_pk_bf16_f32 v7, v7, v113
	v_cvt_pk_bf16_f32 v8, v8, v110
	v_cvt_pk_bf16_f32 v9, v9, v111
	v_add_u32_e32 v0, s4, v52
	v_add_u32_e32 v10, 0x5ea00, v0
	v_ashrrev_i32_e32 v11, 31, v10
	v_lshlrev_b64 v[10:11], 10, v[10:11]
	v_lshl_add_u64 v[10:11], s[50:51], 0, v[10:11]
	v_lshl_add_u64 v[10:11], v[10:11], 0, s[6:7]
	v_lshlrev_b32_e32 v0, 1, v4
	v_lshl_add_u64 v[10:11], v[10:11], 0, v[0:1]
	flat_store_dwordx4 v[10:11], v[6:9]
	ds_read_b32 v6, v29 offset:32
	ds_read_b32 v112, v29 offset:164
	ds_read_b32 v7, v29 offset:296
	ds_read_b32 v113, v29 offset:428
	ds_read_b32 v8, v29 offset:560
	ds_read_b32 v110, v29 offset:692
	ds_read_b32 v9, v29 offset:824
	ds_read_b32 v111, v29 offset:956
	s_waitcnt lgkmcnt(0)
	v_cvt_pk_bf16_f32 v6, v6, v112
	v_cvt_pk_bf16_f32 v7, v7, v113
	v_cvt_pk_bf16_f32 v8, v8, v110
	v_cvt_pk_bf16_f32 v9, v9, v111
	v_add_u32_e32 v10, s4, v53
	v_add_u32_e32 v10, 0x5ea00, v10
	v_ashrrev_i32_e32 v11, 31, v10
	v_lshlrev_b64 v[10:11], 10, v[10:11]
	v_lshl_add_u64 v[10:11], s[50:51], 0, v[10:11]
	v_lshl_add_u64 v[10:11], v[10:11], 0, s[6:7]
	v_lshl_add_u64 v[10:11], v[10:11], 0, v[0:1]
	flat_store_dwordx4 v[10:11], v[6:9]
	ds_read_b32 v6, v29 offset:64
	ds_read_b32 v112, v29 offset:196
	ds_read_b32 v7, v29 offset:328
	ds_read_b32 v113, v29 offset:460
	ds_read_b32 v8, v29 offset:592
	ds_read_b32 v110, v29 offset:724
	ds_read_b32 v9, v29 offset:856
	ds_read_b32 v111, v29 offset:988
	s_waitcnt lgkmcnt(0)
	v_cvt_pk_bf16_f32 v6, v6, v112
	v_cvt_pk_bf16_f32 v7, v7, v113
	v_cvt_pk_bf16_f32 v8, v8, v110
	v_cvt_pk_bf16_f32 v9, v9, v111
	v_add_u32_e32 v10, s4, v54
	v_add_u32_e32 v10, 0x5ea00, v10
	v_ashrrev_i32_e32 v11, 31, v10
	v_lshlrev_b64 v[10:11], 10, v[10:11]
	v_lshl_add_u64 v[10:11], s[50:51], 0, v[10:11]
	v_lshl_add_u64 v[10:11], v[10:11], 0, s[6:7]
	v_lshl_add_u64 v[10:11], v[10:11], 0, v[0:1]
	flat_store_dwordx4 v[10:11], v[6:9]
	ds_read_b32 v8, v29 offset:96
	ds_read_b32 v9, v29 offset:228
	ds_read_b32 v12, v29 offset:360
	ds_read_b32 v13, v29 offset:492
	ds_read_b32 v14, v29 offset:624
	ds_read_b32 v15, v29 offset:756
	ds_read_b32 v16, v29 offset:888
	ds_read_b32 v17, v29 offset:1020
	v_add_u32_e32 v6, s4, v55
	v_add_u32_e32 v6, 0x5ea00, v6
	v_ashrrev_i32_e32 v7, 31, v6
	v_lshlrev_b64 v[6:7], 10, v[6:7]
	v_lshl_add_u64 v[10:11], s[50:51], 0, v[6:7]
	v_lshl_add_u64 v[10:11], v[10:11], 0, s[6:7]
	s_waitcnt lgkmcnt(0)
	v_cvt_pk_bf16_f32 v6, v8, v9
	v_cvt_pk_bf16_f32 v7, v12, v13
	v_cvt_pk_bf16_f32 v8, v14, v15
	v_cvt_pk_bf16_f32 v9, v16, v17
	v_lshl_add_u64 v[10:11], v[10:11], 0, v[0:1]
	flat_store_dwordx4 v[10:11], v[6:9]
	s_waitcnt lgkmcnt(0)

; __device__ __forceinline__ void conv_item(const float* W, int K, int N, int kind, int item, const float* gain, unsigned char* Wb, float* scr, int lane) {
;     const int nblk = N / 32, kb = item / nblk, nb = item - kb * nblk, k0 = 64 * kb, n0 = 32 * nb;
;     float wv_[32];
; #pragma unroll
;     for (int i = 0; i < 32; ++i) wv_[i] = W[(size_t)(k0 + 2 * i + (lane >> 5)) * N + n0 + (lane & 31)];
; __global__ void __launch_bounds__(512, 2) mk_fwd(Args a) {
;     ...
;                     if (r < 256) { conv_item(ap->in[11] + L * 512 * 1024, 512, 1024, 7, r, nullptr, Wb, scr, lane); continue; } r -= 256;
.LBB0_1213:
	s_andn2_b64 vcc, exec, s[4:5]
	s_cbranch_vccnz .LBB0_1215
	s_lshl_b32 s4, s78, 5
	s_and_b32 s6, s4, 0xfffffc00
	v_readlane_b32 s4, v254, 40
	v_readlane_b32 s5, v254, 41
	s_load_dwordx2 s[4:5], s[4:5], 0x58
	s_lshl_b32 s7, s73, 1
	v_lshlrev_b32_e32 v0, 2, v2
	s_waitcnt lgkmcnt(0)
	s_add_u32 s12, s4, s46
	s_addc_u32 s13, s5, s47
	s_add_i32 s4, s7, 0x6c0
	s_and_b32 s92, s4, 0xffffffc0
	s_sub_i32 s4, s75, s6
	s_add_i32 s4, s4, 0xfffa3600
	s_ashr_i32 s5, s4, 31
	s_lshl_b64 s[6:7], s[4:5], 2
	s_add_u32 s6, s12, s6
	v_or_b32_e32 v8, s92, v3
	s_addc_u32 s7, s13, s7
	v_lshl_add_u64 v[6:7], s[6:7], 0, v[0:1]
	v_lshlrev_b32_e32 v0, 10, v8
	v_lshl_add_u64 v[6:7], v[0:1], 2, v[6:7]
	s_movk_i32 s5, 0x2000
	v_add_co_u32_e32 v8, vcc, s5, v6
	s_movk_i32 s5, 0x4000
	s_nop 0
	v_addc_co_u32_e32 v9, vcc, 0, v7, vcc
	global_load_dword v0, v[6:7], off
	global_load_dword v10, v[8:9], off
	v_add_co_u32_e32 v8, vcc, s5, v6
	s_movk_i32 s5, 0x6000
	s_nop 0
	v_addc_co_u32_e32 v9, vcc, 0, v7, vcc
	global_load_dword v11, v[8:9], off
	v_add_co_u32_e32 v8, vcc, s5, v6
	s_mov_b32 s5, 0x8000
	s_nop 0
	v_addc_co_u32_e32 v9, vcc, 0, v7, vcc
	global_load_dword v12, v[8:9], off
	v_add_co_u32_e32 v8, vcc, s5, v6
	s_mov_b32 s5, 0xa000
	s_nop 0
	v_addc_co_u32_e32 v9, vcc, 0, v7, vcc
	global_load_dword v13, v[8:9], off
	v_add_co_u32_e32 v8, vcc, s5, v6
	s_mov_b32 s5, 0xc000
	s_nop 0
	v_addc_co_u32_e32 v9, vcc, 0, v7, vcc
	global_load_dword v14, v[8:9], off
	v_add_co_u32_e32 v8, vcc, s5, v6
	s_mov_b32 s5, 0xe000
	s_nop 0
	v_addc_co_u32_e32 v9, vcc, 0, v7, vcc
	global_load_dword v15, v[8:9], off
	v_add_co_u32_e32 v8, vcc, s5, v6
	s_mov_b32 s5, 0x10000
	s_nop 0
	v_addc_co_u32_e32 v9, vcc, 0, v7, vcc
	global_load_dword v16, v[8:9], off
	v_add_co_u32_e32 v8, vcc, s5, v6
	s_mov_b32 s5, 0x12000
	s_nop 0
	v_addc_co_u32_e32 v9, vcc, 0, v7, vcc
	global_load_dword v17, v[8:9], off
	v_add_co_u32_e32 v8, vcc, s5, v6
	s_mov_b32 s5, 0x14000
	s_nop 0
	v_addc_co_u32_e32 v9, vcc, 0, v7, vcc
	global_load_dword v18, v[8:9], off
	v_add_co_u32_e32 v8, vcc, s5, v6
	s_mov_b32 s5, 0x16000
	s_nop 0
	v_addc_co_u32_e32 v9, vcc, 0, v7, vcc
	global_load_dword v19, v[8:9], off
	v_add_co_u32_e32 v8, vcc, s5, v6
	s_mov_b32 s5, 0x18000
	s_nop 0
	v_addc_co_u32_e32 v9, vcc, 0, v7, vcc
	global_load_dword v20, v[8:9], off
	v_add_co_u32_e32 v8, vcc, s5, v6
	s_mov_b32 s5, 0x1a000
	s_nop 0
	v_addc_co_u32_e32 v9, vcc, 0, v7, vcc
	global_load_dword v21, v[8:9], off
	v_add_co_u32_e32 v8, vcc, s5, v6
	s_mov_b32 s5, 0x1c000
	s_nop 0
	v_addc_co_u32_e32 v9, vcc, 0, v7, vcc
	global_load_dword v22, v[8:9], off
	v_add_co_u32_e32 v8, vcc, s5, v6
	s_mov_b32 s5, 0x1e000
	s_nop 0
	v_addc_co_u32_e32 v9, vcc, 0, v7, vcc
	global_load_dword v23, v[8:9], off
	v_add_co_u32_e32 v8, vcc, s5, v6
	s_mov_b32 s5, 0x20000
	s_nop 0
	v_addc_co_u32_e32 v9, vcc, 0, v7, vcc
	global_load_dword v24, v[8:9], off
	v_add_co_u32_e32 v8, vcc, s5, v6
	s_mov_b32 s5, 0x22000
	s_nop 0
	v_addc_co_u32_e32 v9, vcc, 0, v7, vcc
	global_load_dword v25, v[8:9], off
	v_add_co_u32_e32 v8, vcc, s5, v6
	s_mov_b32 s5, 0x24000
	s_nop 0
	v_addc_co_u32_e32 v9, vcc, 0, v7, vcc
	global_load_dword v26, v[8:9], off
	v_add_co_u32_e32 v8, vcc, s5, v6
	s_mov_b32 s5, 0x26000
	s_nop 0
	v_addc_co_u32_e32 v9, vcc, 0, v7, vcc
	global_load_dword v27, v[8:9], off
	v_add_co_u32_e32 v8, vcc, s5, v6
	s_mov_b32 s5, 0x28000
	s_nop 0
	v_addc_co_u32_e32 v9, vcc, 0, v7, vcc
	global_load_dword v103, v[8:9], off
	v_add_co_u32_e32 v8, vcc, s5, v6
	s_mov_b32 s5, 0x2a000
	s_nop 0
	v_addc_co_u32_e32 v9, vcc, 0, v7, vcc
	global_load_dword v104, v[8:9], off
	v_add_co_u32_e32 v8, vcc, s5, v6
	s_mov_b32 s5, 0x2c000
	s_nop 0
	v_addc_co_u32_e32 v9, vcc, 0, v7, vcc
	global_load_dword v105, v[8:9], off
	v_add_co_u32_e32 v8, vcc, s5, v6
	s_mov_b32 s5, 0x2e000
	s_nop 0
	v_addc_co_u32_e32 v9, vcc, 0, v7, vcc
	global_load_dword v106, v[8:9], off
	v_add_co_u32_e32 v8, vcc, s5, v6
	s_mov_b32 s5, 0x30000
	s_nop 0
	v_addc_co_u32_e32 v9, vcc, 0, v7, vcc
	global_load_dword v107, v[8:9], off
	v_add_co_u32_e32 v8, vcc, s5, v6
	s_mov_b32 s5, 0x32000
	s_nop 0
	v_addc_co_u32_e32 v9, vcc, 0, v7, vcc
	global_load_dword v108, v[8:9], off
	v_add_co_u32_e32 v8, vcc, s5, v6
	s_mov_b32 s5, 0x34000
	s_nop 0
	v_addc_co_u32_e32 v9, vcc, 0, v7, vcc
	global_load_dword v109, v[8:9], off
	v_add_co_u32_e32 v8, vcc, s5, v6
	s_mov_b32 s5, 0x36000
	s_nop 0
	v_addc_co_u32_e32 v9, vcc, 0, v7, vcc
	global_load_dword v110, v[8:9], off
	v_add_co_u32_e32 v8, vcc, s5, v6
	s_mov_b32 s5, 0x38000
	s_nop 0
	v_addc_co_u32_e32 v9, vcc, 0, v7, vcc
	global_load_dword v111, v[8:9], off
	v_add_co_u32_e32 v8, vcc, s5, v6
	s_mov_b32 s5, 0x3a000
	s_nop 0
	v_addc_co_u32_e32 v9, vcc, 0, v7, vcc
	global_load_dword v112, v[8:9], off
	v_add_co_u32_e32 v8, vcc, s5, v6
	s_mov_b32 s5, 0x3c000
	s_nop 0
	v_addc_co_u32_e32 v9, vcc, 0, v7, vcc
	global_load_dword v113, v[8:9], off
	v_add_co_u32_e32 v8, vcc, s5, v6
	s_mov_b32 s5, 0x3e000
	s_nop 0
	v_addc_co_u32_e32 v9, vcc, 0, v7, vcc
	v_add_co_u32_e32 v6, vcc, s5, v6
	global_load_dword v8, v[8:9], off
	s_nop 0
	v_addc_co_u32_e32 v7, vcc, 0, v7, vcc
	global_load_dword v6, v[6:7], off
	s_waitcnt vmcnt(0)
; __device__ __forceinline__ unsigned pk2(float lo, float hi) { f32x2_t v = {lo, hi}; bf16x2_t b = __builtin_convertvector(v, bf16x2_t); return __builtin_bit_cast(unsigned, b); }
; __device__ __forceinline__ void conv_item(const float* W, int K, int N, int kind, int item, const float* gain, unsigned char* Wb, float* scr, int lane) {
;     ...
;     for (int i = 0; i < 32; ++i) scr[(2 * i + (lane >> 5)) * 33 + (lane & 31)] = wv_[i];
;     __builtin_amdgcn_s_waitcnt(0); asm volatile("" ::: "memory");
;     const int c = lane & 7; float gg[8];
; #pragma unroll
;     for (int e = 0; e < 8; ++e) gg[e] = gain ? gain[k0 + 8 * c + e] : 1.0f;
; #pragma unroll
;     for (int j = 0; j < 4; ++j) { const int n = (lane >> 3) + 8 * j; const float* s = scr + (8 * c) * 33 + n;
;         u32x4 o; o.x = pk2(s[0] * gg[0], s[33] * gg[1]); o.y = pk2(s[2 * 33] * gg[2], s[3 * 33] * gg[3]); o.z = pk2(s[4 * 33] * gg[4], s[5 * 33] * gg[5]); o.w = pk2(s[6 * 33] * gg[6], s[7 * 33] * gg[7]);
;         *(u32x4*)(wdst(kind, n0 + n, Wb) + k0 + 8 * c) = o; }
	ds_write2_b32 v5, v0, v10 offset1:66
	ds_write2_b32 v5, v11, v12 offset0:132 offset1:198
	v_add_u32_e32 v0, 0x400, v5
	ds_write2_b32 v0, v13, v14 offset0:8 offset1:74
	ds_write2_b32 v0, v15, v16 offset0:140 offset1:206
	v_add_u32_e32 v0, 0x800, v5
	ds_write2_b32 v0, v17, v18 offset0:16 offset1:82
	ds_write2_b32 v0, v19, v20 offset0:148 offset1:214
	v_add_u32_e32 v0, 0xc00, v5
	ds_write2_b32 v0, v21, v22 offset0:24 offset1:90
	ds_write2_b32 v0, v23, v24 offset0:156 offset1:222
	v_add_u32_e32 v0, 0x1000, v5
	ds_write2_b32 v0, v25, v26 offset0:32 offset1:98
	ds_write2_b32 v0, v27, v103 offset0:164 offset1:230
	v_add_u32_e32 v0, 0x1400, v5
	ds_write2_b32 v0, v104, v105 offset0:40 offset1:106
	ds_write2_b32 v0, v106, v107 offset0:172 offset1:238
	v_add_u32_e32 v0, 0x1800, v5
	ds_write2_b32 v0, v108, v109 offset0:48 offset1:114
	ds_write2_b32 v0, v110, v111 offset0:180 offset1:246
	v_add_u32_e32 v0, 0x1c00, v5
	ds_write2_b32 v0, v112, v113 offset0:56 offset1:122
	ds_write2_b32 v0, v8, v6 offset0:188 offset1:254
	s_waitcnt vmcnt(0) expcnt(0) lgkmcnt(0)
	ds_read_b32 v6, v29
	ds_read_b32 v112, v29 offset:132
	ds_read_b32 v7, v29 offset:264
	ds_read_b32 v113, v29 offset:396
	ds_read_b32 v8, v29 offset:528
	ds_read_b32 v110, v29 offset:660
	ds_read_b32 v9, v29 offset:792
	ds_read_b32 v111, v29 offset:924
	s_lshl_b64 s[6:7], s[92:93], 1
	s_waitcnt lgkmcnt(0)
	v_cvt_pk_bf16_f32 v6, v6, v112
	v_cvt_pk_bf16_f32 v7, v7, v113
	v_cvt_pk_bf16_f32 v8, v8, v110
	v_cvt_pk_bf16_f32 v9, v9, v111
	v_add_u32_e32 v0, s4, v56
	v_add_u32_e32 v10, 0x5ca00, v0
	v_ashrrev_i32_e32 v11, 31, v10
	v_lshlrev_b64 v[10:11], 10, v[10:11]
	v_lshl_add_u64 v[10:11], s[52:53], 0, v[10:11]
	v_lshl_add_u64 v[10:11], v[10:11], 0, s[6:7]
	v_lshlrev_b32_e32 v0, 1, v4
	v_lshl_add_u64 v[10:11], v[10:11], 0, v[0:1]
	flat_store_dwordx4 v[10:11], v[6:9]
	ds_read_b32 v6, v29 offset:32
	ds_read_b32 v112, v29 offset:164
	ds_read_b32 v7, v29 offset:296
	ds_read_b32 v113, v29 offset:428
	ds_read_b32 v8, v29 offset:560
	ds_read_b32 v110, v29 offset:692
	ds_read_b32 v9, v29 offset:824
	ds_read_b32 v111, v29 offset:956
	s_waitcnt lgkmcnt(0)
	v_cvt_pk_bf16_f32 v6, v6, v112
	v_cvt_pk_bf16_f32 v7, v7, v113
	v_cvt_pk_bf16_f32 v8, v8, v110
	v_cvt_pk_bf16_f32 v9, v9, v111
	v_add_u32_e32 v10, s4, v57
	v_add_u32_e32 v10, 0x5ca00, v10
	v_ashrrev_i32_e32 v11, 31, v10
	v_lshlrev_b64 v[10:11], 10, v[10:11]
	v_lshl_add_u64 v[10:11], s[52:53], 0, v[10:11]
	v_lshl_add_u64 v[10:11], v[10:11], 0, s[6:7]
	v_lshl_add_u64 v[10:11], v[10:11], 0, v[0:1]
	flat_store_dwordx4 v[10:11], v[6:9]
	ds_read_b32 v6, v29 offset:64
	ds_read_b32 v112, v29 offset:196
	ds_read_b32 v7, v29 offset:328
	ds_read_b32 v113, v29 offset:460
	ds_read_b32 v8, v29 offset:592
	ds_read_b32 v110, v29 offset:724
	ds_read_b32 v9, v29 offset:856
	ds_read_b32 v111, v29 offset:988
	s_waitcnt lgkmcnt(0)
	v_cvt_pk_bf16_f32 v6, v6, v112
	v_cvt_pk_bf16_f32 v7, v7, v113
	v_cvt_pk_bf16_f32 v8, v8, v110
	v_cvt_pk_bf16_f32 v9, v9, v111
	v_add_u32_e32 v10, s4, v58
	v_add_u32_e32 v10, 0x5ca00, v10
	v_ashrrev_i32_e32 v11, 31, v10
	v_lshlrev_b64 v[10:11], 10, v[10:11]
	v_lshl_add_u64 v[10:11], s[52:53], 0, v[10:11]
	v_lshl_add_u64 v[10:11], v[10:11], 0, s[6:7]
	v_lshl_add_u64 v[10:11], v[10:11], 0, v[0:1]
	flat_store_dwordx4 v[10:11], v[6:9]
	ds_read_b32 v8, v29 offset:96
	ds_read_b32 v9, v29 offset:228
	ds_read_b32 v12, v29 offset:360
	ds_read_b32 v13, v29 offset:492
	ds_read_b32 v14, v29 offset:624
	ds_read_b32 v15, v29 offset:756
	ds_read_b32 v16, v29 offset:888
	ds_read_b32 v17, v29 offset:1020
	v_add_u32_e32 v6, s4, v59
	v_add_u32_e32 v6, 0x5ca00, v6
	v_ashrrev_i32_e32 v7, 31, v6
	v_lshlrev_b64 v[6:7], 10, v[6:7]
	v_lshl_add_u64 v[10:11], s[52:53], 0, v[6:7]
	v_lshl_add_u64 v[10:11], v[10:11], 0, s[6:7]
	s_waitcnt lgkmcnt(0)
	v_cvt_pk_bf16_f32 v6, v8, v9
	v_cvt_pk_bf16_f32 v7, v12, v13
	v_cvt_pk_bf16_f32 v8, v14, v15
	v_cvt_pk_bf16_f32 v9, v16, v17
	v_lshl_add_u64 v[10:11], v[10:11], 0, v[0:1]
	flat_store_dwordx4 v[10:11], v[6:9]
	s_waitcnt lgkmcnt(0)

; __device__ __forceinline__ void conv_item(const float* W, int K, int N, int kind, int item, const float* gain, unsigned char* Wb, float* scr, int lane) {
;     const int nblk = N / 32, kb = item / nblk, nb = item - kb * nblk, k0 = 64 * kb, n0 = 32 * nb;
;     float wv_[32];
; #pragma unroll
;     for (int i = 0; i < 32; ++i) wv_[i] = W[(size_t)(k0 + 2 * i + (lane >> 5)) * N + n0 + (lane & 31)];
; __global__ void __launch_bounds__(512, 2) mk_fwd(Args a) {
;     ...
;                     if (r < 512) { conv_item(ap->in[16] + L * 1024 * 1024, 1024, 1024, 10, r, nullptr, Wb, scr, lane); continue; } r -= 512;
.LBB0_1216:
	s_andn2_b64 vcc, exec, s[4:5]
	s_cbranch_vccnz .LBB0_1218
	s_lshl_b32 s4, s79, 5
	s_and_b32 s6, s4, 0xfffffc00
	v_readlane_b32 s4, v254, 40
	v_readlane_b32 s5, v254, 41
	s_load_dwordx2 s[4:5], s[4:5], 0x80
	s_lshl_b32 s7, s73, 1
	v_lshlrev_b32_e32 v0, 2, v2
	s_waitcnt lgkmcnt(0)
	s_add_u32 s12, s4, s54
	s_addc_u32 s13, s5, s55
	s_add_i32 s4, s7, 0xac0
	s_and_b32 s92, s4, 0xffffffc0
	s_sub_i32 s4, s75, s6
	s_add_i32 s4, s4, 0xfffa7600
	s_ashr_i32 s5, s4, 31
	s_lshl_b64 s[6:7], s[4:5], 2
	s_add_u32 s6, s12, s6
	v_or_b32_e32 v8, s92, v3
	s_addc_u32 s7, s13, s7
	v_lshl_add_u64 v[6:7], s[6:7], 0, v[0:1]
	v_lshlrev_b32_e32 v0, 10, v8
	v_lshl_add_u64 v[6:7], v[0:1], 2, v[6:7]
	s_movk_i32 s5, 0x2000
	v_add_co_u32_e32 v8, vcc, s5, v6
	s_movk_i32 s5, 0x4000
	s_nop 0
	v_addc_co_u32_e32 v9, vcc, 0, v7, vcc
	global_load_dword v0, v[6:7], off
	global_load_dword v10, v[8:9], off
	v_add_co_u32_e32 v8, vcc, s5, v6
	s_movk_i32 s5, 0x6000
	s_nop 0
	v_addc_co_u32_e32 v9, vcc, 0, v7, vcc
	global_load_dword v11, v[8:9], off
	v_add_co_u32_e32 v8, vcc, s5, v6
	s_mov_b32 s5, 0x8000
	s_nop 0
	v_addc_co_u32_e32 v9, vcc, 0, v7, vcc
	global_load_dword v12, v[8:9], off
	v_add_co_u32_e32 v8, vcc, s5, v6
	s_mov_b32 s5, 0xa000
	s_nop 0
	v_addc_co_u32_e32 v9, vcc, 0, v7, vcc
	global_load_dword v13, v[8:9], off
	v_add_co_u32_e32 v8, vcc, s5, v6
	s_mov_b32 s5, 0xc000
	s_nop 0
	v_addc_co_u32_e32 v9, vcc, 0, v7, vcc
	global_load_dword v14, v[8:9], off
	v_add_co_u32_e32 v8, vcc, s5, v6
	s_mov_b32 s5, 0xe000
	s_nop 0
	v_addc_co_u32_e32 v9, vcc, 0, v7, vcc
	global_load_dword v15, v[8:9], off
	v_add_co_u32_e32 v8, vcc, s5, v6
	s_mov_b32 s5, 0x10000
	s_nop 0
	v_addc_co_u32_e32 v9, vcc, 0, v7, vcc
	global_load_dword v16, v[8:9], off
	v_add_co_u32_e32 v8, vcc, s5, v6
	s_mov_b32 s5, 0x12000
	s_nop 0
	v_addc_co_u32_e32 v9, vcc, 0, v7, vcc
	global_load_dword v17, v[8:9], off
	v_add_co_u32_e32 v8, vcc, s5, v6
	s_mov_b32 s5, 0x14000
	s_nop 0
	v_addc_co_u32_e32 v9, vcc, 0, v7, vcc
	global_load_dword v18, v[8:9], off
	v_add_co_u32_e32 v8, vcc, s5, v6
	s_mov_b32 s5, 0x16000
	s_nop 0
	v_addc_co_u32_e32 v9, vcc, 0, v7, vcc
	global_load_dword v19, v[8:9], off
	v_add_co_u32_e32 v8, vcc, s5, v6
	s_mov_b32 s5, 0x18000
	s_nop 0
	v_addc_co_u32_e32 v9, vcc, 0, v7, vcc
	global_load_dword v20, v[8:9], off
	v_add_co_u32_e32 v8, vcc, s5, v6
	s_mov_b32 s5, 0x1a000
	s_nop 0
	v_addc_co_u32_e32 v9, vcc, 0, v7, vcc
	global_load_dword v21, v[8:9], off
	v_add_co_u32_e32 v8, vcc, s5, v6
	s_mov_b32 s5, 0x1c000
	s_nop 0
	v_addc_co_u32_e32 v9, vcc, 0, v7, vcc
	global_load_dword v22, v[8:9], off
	v_add_co_u32_e32 v8, vcc, s5, v6
	s_mov_b32 s5, 0x1e000
	s_nop 0
	v_addc_co_u32_e32 v9, vcc, 0, v7, vcc
	global_load_dword v23, v[8:9], off
	v_add_co_u32_e32 v8, vcc, s5, v6
	s_mov_b32 s5, 0x20000
	s_nop 0
	v_addc_co_u32_e32 v9, vcc, 0, v7, vcc
	global_load_dword v24, v[8:9], off
	v_add_co_u32_e32 v8, vcc, s5, v6
	s_mov_b32 s5, 0x22000
	s_nop 0
	v_addc_co_u32_e32 v9, vcc, 0, v7, vcc
	global_load_dword v25, v[8:9], off
	v_add_co_u32_e32 v8, vcc, s5, v6
	s_mov_b32 s5, 0x24000
	s_nop 0
	v_addc_co_u32_e32 v9, vcc, 0, v7, vcc
	global_load_dword v26, v[8:9], off
	v_add_co_u32_e32 v8, vcc, s5, v6
	s_mov_b32 s5, 0x26000
	s_nop 0
	v_addc_co_u32_e32 v9, vcc, 0, v7, vcc
	global_load_dword v27, v[8:9], off
	v_add_co_u32_e32 v8, vcc, s5, v6
	s_mov_b32 s5, 0x28000
	s_nop 0
	v_addc_co_u32_e32 v9, vcc, 0, v7, vcc
	global_load_dword v103, v[8:9], off
	v_add_co_u32_e32 v8, vcc, s5, v6
	s_mov_b32 s5, 0x2a000
	s_nop 0
	v_addc_co_u32_e32 v9, vcc, 0, v7, vcc
	global_load_dword v104, v[8:9], off
	v_add_co_u32_e32 v8, vcc, s5, v6
	s_mov_b32 s5, 0x2c000
	s_nop 0
	v_addc_co_u32_e32 v9, vcc, 0, v7, vcc
	global_load_dword v105, v[8:9], off
	v_add_co_u32_e32 v8, vcc, s5, v6
	s_mov_b32 s5, 0x2e000
	s_nop 0
	v_addc_co_u32_e32 v9, vcc, 0, v7, vcc
	global_load_dword v106, v[8:9], off
	v_add_co_u32_e32 v8, vcc, s5, v6
	s_mov_b32 s5, 0x30000
	s_nop 0
	v_addc_co_u32_e32 v9, vcc, 0, v7, vcc
	global_load_dword v107, v[8:9], off
	v_add_co_u32_e32 v8, vcc, s5, v6
	s_mov_b32 s5, 0x32000
	s_nop 0
	v_addc_co_u32_e32 v9, vcc, 0, v7, vcc
	global_load_dword v108, v[8:9], off
	v_add_co_u32_e32 v8, vcc, s5, v6
	s_mov_b32 s5, 0x34000
	s_nop 0
	v_addc_co_u32_e32 v9, vcc, 0, v7, vcc
	global_load_dword v109, v[8:9], off
	v_add_co_u32_e32 v8, vcc, s5, v6
	s_mov_b32 s5, 0x36000
	s_nop 0
	v_addc_co_u32_e32 v9, vcc, 0, v7, vcc
	global_load_dword v110, v[8:9], off
	v_add_co_u32_e32 v8, vcc, s5, v6
	s_mov_b32 s5, 0x38000
	s_nop 0
	v_addc_co_u32_e32 v9, vcc, 0, v7, vcc
	global_load_dword v111, v[8:9], off
	v_add_co_u32_e32 v8, vcc, s5, v6
	s_mov_b32 s5, 0x3a000
	s_nop 0
	v_addc_co_u32_e32 v9, vcc, 0, v7, vcc
	global_load_dword v112, v[8:9], off
	v_add_co_u32_e32 v8, vcc, s5, v6
	s_mov_b32 s5, 0x3c000
	s_nop 0
	v_addc_co_u32_e32 v9, vcc, 0, v7, vcc
	global_load_dword v113, v[8:9], off
	v_add_co_u32_e32 v8, vcc, s5, v6
	s_mov_b32 s5, 0x3e000
	s_nop 0
	v_addc_co_u32_e32 v9, vcc, 0, v7, vcc
	v_add_co_u32_e32 v6, vcc, s5, v6
	global_load_dword v8, v[8:9], off
	s_nop 0
	v_addc_co_u32_e32 v7, vcc, 0, v7, vcc
	global_load_dword v6, v[6:7], off
	s_waitcnt vmcnt(0)
; __device__ __forceinline__ unsigned pk2(float lo, float hi) { f32x2_t v = {lo, hi}; bf16x2_t b = __builtin_convertvector(v, bf16x2_t); return __builtin_bit_cast(unsigned, b); }
; __device__ __forceinline__ void conv_item(const float* W, int K, int N, int kind, int item, const float* gain, unsigned char* Wb, float* scr, int lane) {
;     ...
;     for (int i = 0; i < 32; ++i) scr[(2 * i + (lane >> 5)) * 33 + (lane & 31)] = wv_[i];
;     __builtin_amdgcn_s_waitcnt(0); asm volatile("" ::: "memory");
;     const int c = lane & 7; float gg[8];
; #pragma unroll
;     for (int e = 0; e < 8; ++e) gg[e] = gain ? gain[k0 + 8 * c + e] : 1.0f;
; #pragma unroll
;     for (int j = 0; j < 4; ++j) { const int n = (lane >> 3) + 8 * j; const float* s = scr + (8 * c) * 33 + n;
;         u32x4 o; o.x = pk2(s[0] * gg[0], s[33] * gg[1]); o.y = pk2(s[2 * 33] * gg[2], s[3 * 33] * gg[3]); o.z = pk2(s[4 * 33] * gg[4], s[5 * 33] * gg[5]); o.w = pk2(s[6 * 33] * gg[6], s[7 * 33] * gg[7]);
;         *(u32x4*)(wdst(kind, n0 + n, Wb) + k0 + 8 * c) = o; }
	ds_write2_b32 v5, v0, v10 offset1:66
	ds_write2_b32 v5, v11, v12 offset0:132 offset1:198
	v_add_u32_e32 v0, 0x400, v5
	ds_write2_b32 v0, v13, v14 offset0:8 offset1:74
	ds_write2_b32 v0, v15, v16 offset0:140 offset1:206
	v_add_u32_e32 v0, 0x800, v5
	ds_write2_b32 v0, v17, v18 offset0:16 offset1:82
	ds_write2_b32 v0, v19, v20 offset0:148 offset1:214
	v_add_u32_e32 v0, 0xc00, v5
	ds_write2_b32 v0, v21, v22 offset0:24 offset1:90
	ds_write2_b32 v0, v23, v24 offset0:156 offset1:222
	v_add_u32_e32 v0, 0x1000, v5
	ds_write2_b32 v0, v25, v26 offset0:32 offset1:98
	ds_write2_b32 v0, v27, v103 offset0:164 offset1:230
	v_add_u32_e32 v0, 0x1400, v5
	ds_write2_b32 v0, v104, v105 offset0:40 offset1:106
	ds_write2_b32 v0, v106, v107 offset0:172 offset1:238
	v_add_u32_e32 v0, 0x1800, v5
	ds_write2_b32 v0, v108, v109 offset0:48 offset1:114
	ds_write2_b32 v0, v110, v111 offset0:180 offset1:246
	v_add_u32_e32 v0, 0x1c00, v5
	ds_write2_b32 v0, v112, v113 offset0:56 offset1:122
	ds_write2_b32 v0, v8, v6 offset0:188 offset1:254
	s_waitcnt vmcnt(0) expcnt(0) lgkmcnt(0)
	ds_read_b32 v6, v29
	ds_read_b32 v112, v29 offset:132
	ds_read_b32 v7, v29 offset:264
	ds_read_b32 v113, v29 offset:396
	ds_read_b32 v8, v29 offset:528
	ds_read_b32 v110, v29 offset:660
	ds_read_b32 v9, v29 offset:792
	ds_read_b32 v111, v29 offset:924
	s_lshl_b64 s[6:7], s[92:93], 1
	s_waitcnt lgkmcnt(0)
	v_cvt_pk_bf16_f32 v6, v6, v112
	v_cvt_pk_bf16_f32 v7, v7, v113
	v_cvt_pk_bf16_f32 v8, v8, v110
	v_cvt_pk_bf16_f32 v9, v9, v111
	v_add_u32_e32 v0, s4, v60
	v_add_u32_e32 v10, 0x58a00, v0
	v_ashrrev_i32_e32 v11, 31, v10
	v_lshlrev_b64 v[10:11], 11, v[10:11]
	v_lshl_add_u64 v[10:11], s[56:57], 0, v[10:11]
	v_lshl_add_u64 v[10:11], v[10:11], 0, s[6:7]
	v_lshlrev_b32_e32 v0, 1, v4
	v_lshl_add_u64 v[10:11], v[10:11], 0, v[0:1]
	flat_store_dwordx4 v[10:11], v[6:9]
	ds_read_b32 v6, v29 offset:32
	ds_read_b32 v112, v29 offset:164
	ds_read_b32 v7, v29 offset:296
	ds_read_b32 v113, v29 offset:428
	ds_read_b32 v8, v29 offset:560
	ds_read_b32 v110, v29 offset:692
	ds_read_b32 v9, v29 offset:824
	ds_read_b32 v111, v29 offset:956
	s_waitcnt lgkmcnt(0)
	v_cvt_pk_bf16_f32 v6, v6, v112
	v_cvt_pk_bf16_f32 v7, v7, v113
	v_cvt_pk_bf16_f32 v8, v8, v110
	v_cvt_pk_bf16_f32 v9, v9, v111
	v_add_u32_e32 v10, s4, v61
	v_add_u32_e32 v10, 0x58a00, v10
	v_ashrrev_i32_e32 v11, 31, v10
	v_lshlrev_b64 v[10:11], 11, v[10:11]
	v_lshl_add_u64 v[10:11], s[56:57], 0, v[10:11]
	v_lshl_add_u64 v[10:11], v[10:11], 0, s[6:7]
	v_lshl_add_u64 v[10:11], v[10:11], 0, v[0:1]
	flat_store_dwordx4 v[10:11], v[6:9]
	ds_read_b32 v6, v29 offset:64
	ds_read_b32 v112, v29 offset:196
	ds_read_b32 v7, v29 offset:328
	ds_read_b32 v113, v29 offset:460
	ds_read_b32 v8, v29 offset:592
	ds_read_b32 v110, v29 offset:724
	ds_read_b32 v9, v29 offset:856
	ds_read_b32 v111, v29 offset:988
	s_waitcnt lgkmcnt(0)
	v_cvt_pk_bf16_f32 v6, v6, v112
	v_cvt_pk_bf16_f32 v7, v7, v113
	v_cvt_pk_bf16_f32 v8, v8, v110
	v_cvt_pk_bf16_f32 v9, v9, v111
	v_add_u32_e32 v10, s4, v62
	v_add_u32_e32 v10, 0x58a00, v10
	v_ashrrev_i32_e32 v11, 31, v10
	v_lshlrev_b64 v[10:11], 11, v[10:11]
	v_lshl_add_u64 v[10:11], s[56:57], 0, v[10:11]
	v_lshl_add_u64 v[10:11], v[10:11], 0, s[6:7]
	v_lshl_add_u64 v[10:11], v[10:11], 0, v[0:1]
	flat_store_dwordx4 v[10:11], v[6:9]
	ds_read_b32 v8, v29 offset:96
	ds_read_b32 v9, v29 offset:228
	ds_read_b32 v12, v29 offset:360
	ds_read_b32 v13, v29 offset:492
	ds_read_b32 v14, v29 offset:624
	ds_read_b32 v15, v29 offset:756
	ds_read_b32 v16, v29 offset:888
	ds_read_b32 v17, v29 offset:1020
	v_add_u32_e32 v6, s4, v63
	v_add_u32_e32 v6, 0x58a00, v6
	v_ashrrev_i32_e32 v7, 31, v6
	v_lshlrev_b64 v[6:7], 11, v[6:7]
	v_lshl_add_u64 v[10:11], s[56:57], 0, v[6:7]
	v_lshl_add_u64 v[10:11], v[10:11], 0, s[6:7]
	s_waitcnt lgkmcnt(0)
	v_cvt_pk_bf16_f32 v6, v8, v9
	v_cvt_pk_bf16_f32 v7, v12, v13
	v_cvt_pk_bf16_f32 v8, v14, v15
	v_cvt_pk_bf16_f32 v9, v16, v17
	v_lshl_add_u64 v[10:11], v[10:11], 0, v[0:1]
	flat_store_dwordx4 v[10:11], v[6:9]
	s_waitcnt lgkmcnt(0)

; __device__ __forceinline__ void conv_item(const float* W, int K, int N, int kind, int item, const float* gain, unsigned char* Wb, float* scr, int lane) {
;     const int nblk = N / 32, kb = item / nblk, nb = item - kb * nblk, k0 = 64 * kb, n0 = 32 * nb;
;     float wv_[32];
; #pragma unroll
;     for (int i = 0; i < 32; ++i) wv_[i] = W[(size_t)(k0 + 2 * i + (lane >> 5)) * N + n0 + (lane & 31)];
; __global__ void __launch_bounds__(512, 2) mk_fwd(Args a) {
;     ...
;                     if (r < 1408) { conv_item(ap->in[4] + L * 2816 * 1024, 2816, 1024, 1, r, nullptr, Wb, scr, lane); continue; } r -= 1408;
.LBB0_1219:
	s_andn2_b64 vcc, exec, s[4:5]
	s_cbranch_vccnz .LBB0_1221
	s_lshl_b32 s4, s80, 5
	s_and_b32 s6, s4, 0xfffffc00
	v_readlane_b32 s4, v254, 40
	v_readlane_b32 s5, v254, 41
	s_load_dwordx2 s[4:5], s[4:5], 0x20
	s_lshl_b32 s7, s73, 1
	v_lshlrev_b32_e32 v0, 2, v2
	s_waitcnt lgkmcnt(0)
	s_add_u32 s12, s4, s68
	s_addc_u32 s13, s5, s29
	s_add_i32 s4, s7, 0x20c0
	s_and_b32 s92, s4, 0xffffffc0
	s_sub_i32 s4, s75, s6
	s_add_i32 s4, s4, 0xfffbd600
	s_ashr_i32 s5, s4, 31
	s_lshl_b64 s[6:7], s[4:5], 2
	s_add_u32 s6, s12, s6
	v_or_b32_e32 v8, s92, v3
	s_addc_u32 s7, s13, s7
	v_lshl_add_u64 v[6:7], s[6:7], 0, v[0:1]
	v_lshlrev_b32_e32 v0, 10, v8
	v_lshl_add_u64 v[6:7], v[0:1], 2, v[6:7]
	s_movk_i32 s5, 0x2000
	v_add_co_u32_e32 v8, vcc, s5, v6
	s_movk_i32 s5, 0x4000
	s_nop 0
	v_addc_co_u32_e32 v9, vcc, 0, v7, vcc
	global_load_dword v0, v[6:7], off
	global_load_dword v10, v[8:9], off
	v_add_co_u32_e32 v8, vcc, s5, v6
	s_movk_i32 s5, 0x6000
	s_nop 0
	v_addc_co_u32_e32 v9, vcc, 0, v7, vcc
	global_load_dword v11, v[8:9], off
	v_add_co_u32_e32 v8, vcc, s5, v6
	s_mov_b32 s5, 0x8000
	s_nop 0
	v_addc_co_u32_e32 v9, vcc, 0, v7, vcc
	global_load_dword v12, v[8:9], off
	v_add_co_u32_e32 v8, vcc, s5, v6
	s_mov_b32 s5, 0xa000
	s_nop 0
	v_addc_co_u32_e32 v9, vcc, 0, v7, vcc
	global_load_dword v13, v[8:9], off
	v_add_co_u32_e32 v8, vcc, s5, v6
	s_mov_b32 s5, 0xc000
	s_nop 0
	v_addc_co_u32_e32 v9, vcc, 0, v7, vcc
	global_load_dword v14, v[8:9], off
	v_add_co_u32_e32 v8, vcc, s5, v6
	s_mov_b32 s5, 0xe000
	s_nop 0
	v_addc_co_u32_e32 v9, vcc, 0, v7, vcc
	global_load_dword v15, v[8:9], off
	v_add_co_u32_e32 v8, vcc, s5, v6
	s_mov_b32 s5, 0x10000
	s_nop 0
	v_addc_co_u32_e32 v9, vcc, 0, v7, vcc
	global_load_dword v16, v[8:9], off
	v_add_co_u32_e32 v8, vcc, s5, v6
	s_mov_b32 s5, 0x12000
	s_nop 0
	v_addc_co_u32_e32 v9, vcc, 0, v7, vcc
	global_load_dword v17, v[8:9], off
	v_add_co_u32_e32 v8, vcc, s5, v6
	s_mov_b32 s5, 0x14000
	s_nop 0
	v_addc_co_u32_e32 v9, vcc, 0, v7, vcc
	global_load_dword v18, v[8:9], off
	v_add_co_u32_e32 v8, vcc, s5, v6
	s_mov_b32 s5, 0x16000
	s_nop 0
	v_addc_co_u32_e32 v9, vcc, 0, v7, vcc
	global_load_dword v19, v[8:9], off
	v_add_co_u32_e32 v8, vcc, s5, v6
	s_mov_b32 s5, 0x18000
	s_nop 0
	v_addc_co_u32_e32 v9, vcc, 0, v7, vcc
	global_load_dword v20, v[8:9], off
	v_add_co_u32_e32 v8, vcc, s5, v6
	s_mov_b32 s5, 0x1a000
	s_nop 0
	v_addc_co_u32_e32 v9, vcc, 0, v7, vcc
	global_load_dword v21, v[8:9], off
	v_add_co_u32_e32 v8, vcc, s5, v6
	s_mov_b32 s5, 0x1c000
	s_nop 0
	v_addc_co_u32_e32 v9, vcc, 0, v7, vcc
	global_load_dword v22, v[8:9], off
	v_add_co_u32_e32 v8, vcc, s5, v6
	s_mov_b32 s5, 0x1e000
	s_nop 0
	v_addc_co_u32_e32 v9, vcc, 0, v7, vcc
	global_load_dword v23, v[8:9], off
	v_add_co_u32_e32 v8, vcc, s5, v6
	s_mov_b32 s5, 0x20000
	s_nop 0
	v_addc_co_u32_e32 v9, vcc, 0, v7, vcc
	global_load_dword v24, v[8:9], off
	v_add_co_u32_e32 v8, vcc, s5, v6
	s_mov_b32 s5, 0x22000
	s_nop 0
	v_addc_co_u32_e32 v9, vcc, 0, v7, vcc
	global_load_dword v25, v[8:9], off
	v_add_co_u32_e32 v8, vcc, s5, v6
	s_mov_b32 s5, 0x24000
	s_nop 0
	v_addc_co_u32_e32 v9, vcc, 0, v7, vcc
	global_load_dword v26, v[8:9], off
	v_add_co_u32_e32 v8, vcc, s5, v6
	s_mov_b32 s5, 0x26000
	s_nop 0
	v_addc_co_u32_e32 v9, vcc, 0, v7, vcc
	global_load_dword v27, v[8:9], off
	v_add_co_u32_e32 v8, vcc, s5, v6
	s_mov_b32 s5, 0x28000
	s_nop 0
	v_addc_co_u32_e32 v9, vcc, 0, v7, vcc
	global_load_dword v103, v[8:9], off
	v_add_co_u32_e32 v8, vcc, s5, v6
	s_mov_b32 s5, 0x2a000
	s_nop 0
	v_addc_co_u32_e32 v9, vcc, 0, v7, vcc
	global_load_dword v104, v[8:9], off
	v_add_co_u32_e32 v8, vcc, s5, v6
	s_mov_b32 s5, 0x2c000
	s_nop 0
	v_addc_co_u32_e32 v9, vcc, 0, v7, vcc
	global_load_dword v105, v[8:9], off
	v_add_co_u32_e32 v8, vcc, s5, v6
	s_mov_b32 s5, 0x2e000
	s_nop 0
	v_addc_co_u32_e32 v9, vcc, 0, v7, vcc
	global_load_dword v106, v[8:9], off
	v_add_co_u32_e32 v8, vcc, s5, v6
	s_mov_b32 s5, 0x30000
	s_nop 0
	v_addc_co_u32_e32 v9, vcc, 0, v7, vcc
	global_load_dword v107, v[8:9], off
	v_add_co_u32_e32 v8, vcc, s5, v6
	s_mov_b32 s5, 0x32000
	s_nop 0
	v_addc_co_u32_e32 v9, vcc, 0, v7, vcc
	global_load_dword v108, v[8:9], off
	v_add_co_u32_e32 v8, vcc, s5, v6
	s_mov_b32 s5, 0x34000
	s_nop 0
	v_addc_co_u32_e32 v9, vcc, 0, v7, vcc
	global_load_dword v109, v[8:9], off
	v_add_co_u32_e32 v8, vcc, s5, v6
	s_mov_b32 s5, 0x36000
	s_nop 0
	v_addc_co_u32_e32 v9, vcc, 0, v7, vcc
	global_load_dword v110, v[8:9], off
	v_add_co_u32_e32 v8, vcc, s5, v6
	s_mov_b32 s5, 0x38000
	s_nop 0
	v_addc_co_u32_e32 v9, vcc, 0, v7, vcc
	global_load_dword v111, v[8:9], off
	v_add_co_u32_e32 v8, vcc, s5, v6
	s_mov_b32 s5, 0x3a000
	s_nop 0
	v_addc_co_u32_e32 v9, vcc, 0, v7, vcc
	global_load_dword v112, v[8:9], off
	v_add_co_u32_e32 v8, vcc, s5, v6
	s_mov_b32 s5, 0x3c000
	s_nop 0
	v_addc_co_u32_e32 v9, vcc, 0, v7, vcc
	global_load_dword v113, v[8:9], off
	v_add_co_u32_e32 v8, vcc, s5, v6
	s_mov_b32 s5, 0x3e000
	s_nop 0
	v_addc_co_u32_e32 v9, vcc, 0, v7, vcc
	v_add_co_u32_e32 v6, vcc, s5, v6
	global_load_dword v8, v[8:9], off
	s_nop 0
	v_addc_co_u32_e32 v7, vcc, 0, v7, vcc
	global_load_dword v6, v[6:7], off
	s_waitcnt vmcnt(0)
; __device__ __forceinline__ unsigned pk2(float lo, float hi) { f32x2_t v = {lo, hi}; bf16x2_t b = __builtin_convertvector(v, bf16x2_t); return __builtin_bit_cast(unsigned, b); }
; __device__ __forceinline__ void conv_item(const float* W, int K, int N, int kind, int item, const float* gain, unsigned char* Wb, float* scr, int lane) {
;     ...
;     for (int i = 0; i < 32; ++i) scr[(2 * i + (lane >> 5)) * 33 + (lane & 31)] = wv_[i];
;     __builtin_amdgcn_s_waitcnt(0); asm volatile("" ::: "memory");
;     const int c = lane & 7; float gg[8];
; #pragma unroll
;     for (int e = 0; e < 8; ++e) gg[e] = gain ? gain[k0 + 8 * c + e] : 1.0f;
; #pragma unroll
;     for (int j = 0; j < 4; ++j) { const int n = (lane >> 3) + 8 * j; const float* s = scr + (8 * c) * 33 + n;
;         u32x4 o; o.x = pk2(s[0] * gg[0], s[33] * gg[1]); o.y = pk2(s[2 * 33] * gg[2], s[3 * 33] * gg[3]); o.z = pk2(s[4 * 33] * gg[4], s[5 * 33] * gg[5]); o.w = pk2(s[6 * 33] * gg[6], s[7 * 33] * gg[7]);
;         *(u32x4*)(wdst(kind, n0 + n, Wb) + k0 + 8 * c) = o; }
	ds_write2_b32 v5, v0, v10 offset1:66
	ds_write2_b32 v5, v11, v12 offset0:132 offset1:198
	v_add_u32_e32 v0, 0x400, v5
	ds_write2_b32 v0, v13, v14 offset0:8 offset1:74
	ds_write2_b32 v0, v15, v16 offset0:140 offset1:206
	v_add_u32_e32 v0, 0x800, v5
	ds_write2_b32 v0, v17, v18 offset0:16 offset1:82
	ds_write2_b32 v0, v19, v20 offset0:148 offset1:214
	v_add_u32_e32 v0, 0xc00, v5
	ds_write2_b32 v0, v21, v22 offset0:24 offset1:90
	ds_write2_b32 v0, v23, v24 offset0:156 offset1:222
	v_add_u32_e32 v0, 0x1000, v5
	ds_write2_b32 v0, v25, v26 offset0:32 offset1:98
	ds_write2_b32 v0, v27, v103 offset0:164 offset1:230
	v_add_u32_e32 v0, 0x1400, v5
	ds_write2_b32 v0, v104, v105 offset0:40 offset1:106
	ds_write2_b32 v0, v106, v107 offset0:172 offset1:238
	v_add_u32_e32 v0, 0x1800, v5
	ds_write2_b32 v0, v108, v109 offset0:48 offset1:114
	ds_write2_b32 v0, v110, v111 offset0:180 offset1:246
	v_add_u32_e32 v0, 0x1c00, v5
	ds_write2_b32 v0, v112, v113 offset0:56 offset1:122
	ds_write2_b32 v0, v8, v6 offset0:188 offset1:254
	s_waitcnt vmcnt(0) expcnt(0) lgkmcnt(0)
	ds_read_b32 v0, v29
	ds_read_b32 v6, v29 offset:132
	v_mov_b64_e32 v[10:11], s[58:59]
	s_movk_i32 s5, 0x1600
	v_add_u32_e32 v16, s4, v67
	v_add_u32_e32 v16, 0x42a00, v16
	s_waitcnt lgkmcnt(0)
	v_cvt_pk_bf16_f32 v6, v0, v6
	ds_read_b32 v0, v29 offset:264
	ds_read_b32 v7, v29 offset:396
	s_waitcnt lgkmcnt(0)
	v_cvt_pk_bf16_f32 v7, v0, v7
	ds_read_b32 v0, v29 offset:528
	ds_read_b32 v8, v29 offset:660
	s_waitcnt lgkmcnt(0)
	v_cvt_pk_bf16_f32 v8, v0, v8
	ds_read_b32 v0, v29 offset:792
	ds_read_b32 v9, v29 offset:924
	s_waitcnt lgkmcnt(0)
	v_cvt_pk_bf16_f32 v9, v0, v9
	v_add_u32_e32 v0, s4, v64
	v_add_u32_e32 v0, 0x42a00, v0
	v_mad_i64_i32 v[12:13], s[6:7], v0, s5, v[10:11]
	s_lshl_b64 s[6:7], s[92:93], 1
	s_nop 0
	v_lshl_add_u64 v[12:13], v[12:13], 0, s[6:7]
	v_lshlrev_b32_e32 v0, 1, v4
	v_lshl_add_u64 v[12:13], v[12:13], 0, v[0:1]
	flat_store_dwordx4 v[12:13], v[6:9]
	ds_read_b32 v6, v29 offset:32
	ds_read_b32 v112, v29 offset:164
	ds_read_b32 v7, v29 offset:296
	ds_read_b32 v113, v29 offset:428
	ds_read_b32 v8, v29 offset:560
	ds_read_b32 v110, v29 offset:692
	ds_read_b32 v9, v29 offset:824
	ds_read_b32 v111, v29 offset:956
	s_waitcnt lgkmcnt(0)
	v_cvt_pk_bf16_f32 v6, v6, v112
	v_cvt_pk_bf16_f32 v7, v7, v113
	v_cvt_pk_bf16_f32 v8, v8, v110
	v_cvt_pk_bf16_f32 v9, v9, v111
	v_add_u32_e32 v12, s4, v65
	v_add_u32_e32 v12, 0x42a00, v12
	v_mad_i64_i32 v[12:13], s[12:13], v12, s5, v[10:11]
	v_lshl_add_u64 v[12:13], v[12:13], 0, s[6:7]
	v_lshl_add_u64 v[12:13], v[12:13], 0, v[0:1]
	flat_store_dwordx4 v[12:13], v[6:9]
	ds_read_b32 v6, v29 offset:64
	ds_read_b32 v112, v29 offset:196
	ds_read_b32 v7, v29 offset:328
	ds_read_b32 v113, v29 offset:460
	ds_read_b32 v8, v29 offset:592
	ds_read_b32 v110, v29 offset:724
	ds_read_b32 v9, v29 offset:856
	ds_read_b32 v111, v29 offset:988
	s_waitcnt lgkmcnt(0)
	v_cvt_pk_bf16_f32 v6, v6, v112
	v_cvt_pk_bf16_f32 v7, v7, v113
	v_cvt_pk_bf16_f32 v8, v8, v110
	v_cvt_pk_bf16_f32 v9, v9, v111
	v_add_u32_e32 v12, s4, v66
	v_add_u32_e32 v12, 0x42a00, v12
	v_mad_i64_i32 v[12:13], s[12:13], v12, s5, v[10:11]
	v_lshl_add_u64 v[12:13], v[12:13], 0, s[6:7]
	v_lshl_add_u64 v[12:13], v[12:13], 0, v[0:1]
	flat_store_dwordx4 v[12:13], v[6:9]
	ds_read_b32 v6, v29 offset:96
	ds_read_b32 v7, v29 offset:228
	ds_read_b32 v8, v29 offset:360
	ds_read_b32 v9, v29 offset:492
	ds_read_b32 v12, v29 offset:624
	ds_read_b32 v13, v29 offset:756
	ds_read_b32 v14, v29 offset:888
	ds_read_b32 v15, v29 offset:1020
	v_mad_i64_i32 v[10:11], s[4:5], v16, s5, v[10:11]
	v_lshl_add_u64 v[10:11], v[10:11], 0, s[6:7]
	s_waitcnt lgkmcnt(0)
	v_cvt_pk_bf16_f32 v6, v6, v7
	v_cvt_pk_bf16_f32 v7, v8, v9
	v_cvt_pk_bf16_f32 v8, v12, v13
	v_cvt_pk_bf16_f32 v9, v14, v15
	v_lshl_add_u64 v[10:11], v[10:11], 0, v[0:1]
	flat_store_dwordx4 v[10:11], v[6:9]
	s_waitcnt lgkmcnt(0)
